# batched epilogue loads (G1/G2/ADD) + in-proj weight transpose: 32 serialized load/wait/ds_write steps per item batched into one wait
# speedup vs baseline: 1.0113x; 1.0113x over previous
.LBB0_59:
	v_mov_b32_e32 v210, 0
	v_mov_b32_e32 v211, 0
	v_mov_b32_e32 v212, 0
	v_mov_b32_e32 v213, 0
	v_mov_b32_e32 v214, 0
	v_mov_b32_e32 v215, 0
	v_mov_b32_e32 v216, 0
	v_mov_b32_e32 v217, 0
	v_mov_b32_e32 v218, 0
	v_mov_b32_e32 v219, 0
	v_mov_b32_e32 v220, 0
	v_mov_b32_e32 v221, 0
	v_mov_b32_e32 v222, 0
	v_mov_b32_e32 v223, 0
	v_mov_b32_e32 v224, 0
	v_mov_b32_e32 v225, 0
	v_mov_b32_e32 v226, 0
	v_mov_b32_e32 v227, 0
	v_mov_b32_e32 v228, 0
	v_mov_b32_e32 v229, 0
	v_mov_b32_e32 v230, 0
	v_mov_b32_e32 v231, 0
	v_mov_b32_e32 v232, 0
	v_mov_b32_e32 v233, 0
	v_mov_b32_e32 v234, 0
	v_mov_b32_e32 v235, 0
	v_mov_b32_e32 v236, 0
	v_mov_b32_e32 v237, 0
	v_mov_b32_e32 v238, 0
	v_mov_b32_e32 v239, 0
	v_mov_b32_e32 v240, 0
	v_mov_b32_e32 v241, 0
	s_and_saveexec_b64 s[8:9], vcc
	v_lshl_add_u64 v[244:245], v[22:23], 0, s[4:5]
	global_load_dword v210, v[244:245], off
	v_lshl_add_u64 v[244:245], v[20:21], 0, s[4:5]
	global_load_dword v211, v[244:245], off
	v_lshl_add_u64 v[244:245], v[18:19], 0, s[4:5]
	global_load_dword v212, v[244:245], off
	v_lshl_add_u64 v[244:245], v[16:17], 0, s[4:5]
	global_load_dword v213, v[244:245], off
	v_lshl_add_u64 v[244:245], v[14:15], 0, s[4:5]
	global_load_dword v214, v[244:245], off
	v_lshl_add_u64 v[244:245], v[12:13], 0, s[4:5]
	global_load_dword v215, v[244:245], off
	v_lshl_add_u64 v[244:245], v[10:11], 0, s[4:5]
	global_load_dword v216, v[244:245], off
	v_lshl_add_u64 v[244:245], v[8:9], 0, s[4:5]
	global_load_dword v217, v[244:245], off
	s_add_u32 s4, s4, 0x4ac00
	s_addc_u32 s5, s5, 0
	v_lshl_add_u64 v[244:245], v[22:23], 0, s[4:5]
	global_load_dword v218, v[244:245], off
	v_lshl_add_u64 v[244:245], v[20:21], 0, s[4:5]
	global_load_dword v219, v[244:245], off
	v_lshl_add_u64 v[244:245], v[18:19], 0, s[4:5]
	global_load_dword v220, v[244:245], off
	v_lshl_add_u64 v[244:245], v[16:17], 0, s[4:5]
	global_load_dword v221, v[244:245], off
	v_lshl_add_u64 v[244:245], v[14:15], 0, s[4:5]
	global_load_dword v222, v[244:245], off
	v_lshl_add_u64 v[244:245], v[12:13], 0, s[4:5]
	global_load_dword v223, v[244:245], off
	v_lshl_add_u64 v[244:245], v[10:11], 0, s[4:5]
	global_load_dword v224, v[244:245], off
	v_lshl_add_u64 v[244:245], v[8:9], 0, s[4:5]
	global_load_dword v225, v[244:245], off
	s_add_u32 s4, s4, 0x4ac00
	s_addc_u32 s5, s5, 0
	v_lshl_add_u64 v[244:245], v[22:23], 0, s[4:5]
	global_load_dword v226, v[244:245], off
	v_lshl_add_u64 v[244:245], v[20:21], 0, s[4:5]
	global_load_dword v227, v[244:245], off
	v_lshl_add_u64 v[244:245], v[18:19], 0, s[4:5]
	global_load_dword v228, v[244:245], off
	v_lshl_add_u64 v[244:245], v[16:17], 0, s[4:5]
	global_load_dword v229, v[244:245], off
	v_lshl_add_u64 v[244:245], v[14:15], 0, s[4:5]
	global_load_dword v230, v[244:245], off
	v_lshl_add_u64 v[244:245], v[12:13], 0, s[4:5]
	global_load_dword v231, v[244:245], off
	v_lshl_add_u64 v[244:245], v[10:11], 0, s[4:5]
	global_load_dword v232, v[244:245], off
	v_lshl_add_u64 v[244:245], v[8:9], 0, s[4:5]
	global_load_dword v233, v[244:245], off
	s_add_u32 s4, s4, 0x4ac00
	s_addc_u32 s5, s5, 0
	v_lshl_add_u64 v[244:245], v[22:23], 0, s[4:5]
	global_load_dword v234, v[244:245], off
	v_lshl_add_u64 v[244:245], v[20:21], 0, s[4:5]
	global_load_dword v235, v[244:245], off
	v_lshl_add_u64 v[244:245], v[18:19], 0, s[4:5]
	global_load_dword v236, v[244:245], off
	v_lshl_add_u64 v[244:245], v[16:17], 0, s[4:5]
	global_load_dword v237, v[244:245], off
	v_lshl_add_u64 v[244:245], v[14:15], 0, s[4:5]
	global_load_dword v238, v[244:245], off
	v_lshl_add_u64 v[244:245], v[12:13], 0, s[4:5]
	global_load_dword v239, v[244:245], off
	v_lshl_add_u64 v[244:245], v[10:11], 0, s[4:5]
	global_load_dword v240, v[244:245], off
	v_lshl_add_u64 v[244:245], v[8:9], 0, s[4:5]
	global_load_dword v241, v[244:245], off
	s_add_u32 s4, s4, 0x4ac00
	s_addc_u32 s5, s5, 0
	s_or_b64 exec, exec, s[8:9]
	s_waitcnt vmcnt(0)
	ds_write_b32 v2, v210
	ds_write_b32 v2, v211 offset:264
	ds_write_b32 v2, v212 offset:528
	ds_write_b32 v2, v213 offset:792
	ds_write_b32 v2, v214 offset:1056
	ds_write_b32 v2, v215 offset:1320
	ds_write_b32 v2, v216 offset:1584
	ds_write_b32 v2, v217 offset:1848
	ds_write_b32 v2, v218 offset:2112
	ds_write_b32 v2, v219 offset:2376
	ds_write_b32 v2, v220 offset:2640
	ds_write_b32 v2, v221 offset:2904
	ds_write_b32 v2, v222 offset:3168
	ds_write_b32 v2, v223 offset:3432
	ds_write_b32 v2, v224 offset:3696
	ds_write_b32 v2, v225 offset:3960
	ds_write_b32 v2, v226 offset:4224
	ds_write_b32 v2, v227 offset:4488
	ds_write_b32 v2, v228 offset:4752
	ds_write_b32 v2, v229 offset:5016
	ds_write_b32 v2, v230 offset:5280
	ds_write_b32 v2, v231 offset:5544
	ds_write_b32 v2, v232 offset:5808
	ds_write_b32 v2, v233 offset:6072
	ds_write_b32 v2, v234 offset:6336
	ds_write_b32 v2, v235 offset:6600
	ds_write_b32 v2, v236 offset:6864
	ds_write_b32 v2, v237 offset:7128
	ds_write_b32 v2, v238 offset:7392
	ds_write_b32 v2, v239 offset:7656
	ds_write_b32 v2, v240 offset:7920
	ds_write_b32 v2, v241 offset:8184
	s_branch .LBB0_36

.LBB0_1623:
	s_cmp_lt_i32 s66, 6
	s_cbranch_scc1 .LBB0_1629
	s_cmp_gt_i32 s66, 6
	s_cbranch_scc0 .LBB0_1626
	s_lshl_b32 s6, s83, 8
	v_add_u32_e32 v130, s6, v161
	v_lshl_or_b32 v128, s82, 8, v168
	v_ashrrev_i32_e32 v129, 31, v128
	v_lshlrev_b64 v[128:129], 1, v[128:129]
	v_mov_b32_e32 v132, v130
	v_ashrrev_i32_e32 v133, 31, v132
	v_mul_lo_u32 v136, s42, v133
	v_mul_lo_u32 v131, s43, v132
	v_mad_u64_u32 v[134:135], s[8:9], s42, v132, 0
	v_add3_u32 v135, v135, v136, v131
	v_lshl_add_u64 v[134:135], v[134:135], 1, s[46:47]
	v_lshl_add_u64 v[134:135], v[134:135], 0, v[128:129]
	global_load_dwordx4 v[170:173], v[134:135], off
	global_load_dwordx4 v[188:191], v[134:135], off offset:256
	v_or_b32_e32 v132, 16, v130
	v_ashrrev_i32_e32 v133, 31, v132
	v_mul_lo_u32 v136, s42, v133
	v_mul_lo_u32 v131, s43, v132
	v_mad_u64_u32 v[134:135], s[8:9], s42, v132, 0
	v_add3_u32 v135, v135, v136, v131
	v_lshl_add_u64 v[134:135], v[134:135], 1, s[46:47]
	v_lshl_add_u64 v[134:135], v[134:135], 0, v[128:129]
	global_load_dwordx4 v[192:195], v[134:135], off
	global_load_dwordx4 v[196:199], v[134:135], off offset:256
	v_or_b32_e32 v132, 32, v130
	v_ashrrev_i32_e32 v133, 31, v132
	v_mul_lo_u32 v136, s42, v133
	v_mul_lo_u32 v131, s43, v132
	v_mad_u64_u32 v[134:135], s[8:9], s42, v132, 0
	v_add3_u32 v135, v135, v136, v131
	v_lshl_add_u64 v[134:135], v[134:135], 1, s[46:47]
	v_lshl_add_u64 v[134:135], v[134:135], 0, v[128:129]
	global_load_dwordx4 v[204:207], v[134:135], off
	global_load_dwordx4 v[208:211], v[134:135], off offset:256
	v_or_b32_e32 v132, 48, v130
	v_ashrrev_i32_e32 v133, 31, v132
	v_mul_lo_u32 v136, s42, v133
	v_mul_lo_u32 v131, s43, v132
	v_mad_u64_u32 v[134:135], s[8:9], s42, v132, 0
	v_add3_u32 v135, v135, v136, v131
	v_lshl_add_u64 v[134:135], v[134:135], 1, s[46:47]
	v_lshl_add_u64 v[134:135], v[134:135], 0, v[128:129]
	global_load_dwordx4 v[212:215], v[134:135], off
	global_load_dwordx4 v[216:219], v[134:135], off offset:256
	v_add_u32_e32 v132, s6, v164
	v_ashrrev_i32_e32 v133, 31, v132
	v_mul_lo_u32 v136, s42, v133
	v_mul_lo_u32 v131, s43, v132
	v_mad_u64_u32 v[134:135], s[8:9], s42, v132, 0
	v_add3_u32 v135, v135, v136, v131
	v_lshl_add_u64 v[134:135], v[134:135], 1, s[46:47]
	v_lshl_add_u64 v[134:135], v[134:135], 0, v[128:129]
	global_load_dwordx4 v[220:223], v[134:135], off
	global_load_dwordx4 v[224:227], v[134:135], off offset:256
	v_add_u32_e32 v132, s6, v165
	v_ashrrev_i32_e32 v133, 31, v132
	v_mul_lo_u32 v136, s42, v133
	v_mul_lo_u32 v131, s43, v132
	v_mad_u64_u32 v[134:135], s[8:9], s42, v132, 0
	v_add3_u32 v135, v135, v136, v131
	v_lshl_add_u64 v[134:135], v[134:135], 1, s[46:47]
	v_lshl_add_u64 v[134:135], v[134:135], 0, v[128:129]
	global_load_dwordx4 v[228:231], v[134:135], off
	global_load_dwordx4 v[232:235], v[134:135], off offset:256
	v_add_u32_e32 v132, s6, v166
	v_ashrrev_i32_e32 v133, 31, v132
	v_mul_lo_u32 v136, s42, v133
	v_mul_lo_u32 v131, s43, v132
	v_mad_u64_u32 v[134:135], s[8:9], s42, v132, 0
	v_add3_u32 v135, v135, v136, v131
	v_lshl_add_u64 v[134:135], v[134:135], 1, s[46:47]
	v_lshl_add_u64 v[134:135], v[134:135], 0, v[128:129]
	global_load_dwordx4 v[236:239], v[134:135], off
	global_load_dwordx4 v[240:243], v[134:135], off offset:256
	v_add_u32_e32 v132, s6, v167
	v_ashrrev_i32_e32 v133, 31, v132
	v_mul_lo_u32 v136, s42, v133
	v_mul_lo_u32 v131, s43, v132
	v_mad_u64_u32 v[134:135], s[8:9], s42, v132, 0
	v_add3_u32 v135, v135, v136, v131
	v_lshl_add_u64 v[134:135], v[134:135], 1, s[46:47]
	v_lshl_add_u64 v[134:135], v[134:135], 0, v[128:129]
	global_load_dwordx4 v[150:153], v[134:135], off
	global_load_dwordx4 v[154:157], v[134:135], off offset:256
	v_mov_b32_e32 v132, v130
	v_ashrrev_i32_e32 v133, 31, v132
	v_mul_lo_u32 v136, s42, v133
	v_mul_lo_u32 v131, s43, v132
	v_mad_u64_u32 v[158:159], s[8:9], s42, v132, 0
	v_add3_u32 v159, v159, v136, v131
	v_lshl_add_u64 v[158:159], v[158:159], 1, s[46:47]
	v_lshl_add_u64 v[158:159], v[158:159], 0, v[128:129]
	s_waitcnt vmcnt(15)
	v_lshlrev_b32_e32 v200, 16, v170
	v_and_b32_e32 v170, 0xffff0000, v170
	v_lshlrev_b32_e32 v201, 16, v171
	v_and_b32_e32 v171, 0xffff0000, v171
	v_lshlrev_b32_e32 v244, 16, v172
	v_and_b32_e32 v172, 0xffff0000, v172
	v_lshlrev_b32_e32 v245, 16, v173
	v_and_b32_e32 v173, 0xffff0000, v173
	v_add_f32_e32 v200, v124, v200
	v_add_f32_e32 v170, v125, v170
	v_add_f32_e32 v201, v126, v201
	v_add_f32_e32 v171, v127, v171
	v_add_f32_e32 v244, v120, v244
	v_add_f32_e32 v172, v121, v172
	v_add_f32_e32 v245, v122, v245
	v_add_f32_e32 v173, v123, v173
	v_cvt_pk_bf16_f32 v170, v200, v170
	v_cvt_pk_bf16_f32 v171, v201, v171
	v_cvt_pk_bf16_f32 v172, v244, v172
	v_cvt_pk_bf16_f32 v173, v245, v173
	global_store_dwordx4 v[158:159], v[170:173], off
	s_waitcnt vmcnt(15)
	v_lshlrev_b32_e32 v200, 16, v188
	v_and_b32_e32 v188, 0xffff0000, v188
	v_lshlrev_b32_e32 v201, 16, v189
	v_and_b32_e32 v189, 0xffff0000, v189
	v_lshlrev_b32_e32 v244, 16, v190
	v_and_b32_e32 v190, 0xffff0000, v190
	v_lshlrev_b32_e32 v245, 16, v191
	v_and_b32_e32 v191, 0xffff0000, v191
	v_add_f32_e32 v200, v116, v200
	v_add_f32_e32 v188, v117, v188
	v_add_f32_e32 v201, v118, v201
	v_add_f32_e32 v189, v119, v189
	v_add_f32_e32 v244, v112, v244
	v_add_f32_e32 v190, v113, v190
	v_add_f32_e32 v245, v114, v245
	v_add_f32_e32 v191, v115, v191
	v_cvt_pk_bf16_f32 v188, v200, v188
	v_cvt_pk_bf16_f32 v189, v201, v189
	v_cvt_pk_bf16_f32 v190, v244, v190
	v_cvt_pk_bf16_f32 v191, v245, v191
	global_store_dwordx4 v[158:159], v[188:191], off offset:256
	v_or_b32_e32 v132, 16, v130
	v_ashrrev_i32_e32 v133, 31, v132
	v_mul_lo_u32 v136, s42, v133
	v_mul_lo_u32 v131, s43, v132
	v_mad_u64_u32 v[158:159], s[8:9], s42, v132, 0
	v_add3_u32 v159, v159, v136, v131
	v_lshl_add_u64 v[158:159], v[158:159], 1, s[46:47]
	v_lshl_add_u64 v[158:159], v[158:159], 0, v[128:129]
	s_waitcnt vmcnt(15)
	v_lshlrev_b32_e32 v200, 16, v192
	v_and_b32_e32 v192, 0xffff0000, v192
	v_lshlrev_b32_e32 v201, 16, v193
	v_and_b32_e32 v193, 0xffff0000, v193
	v_lshlrev_b32_e32 v244, 16, v194
	v_and_b32_e32 v194, 0xffff0000, v194
	v_lshlrev_b32_e32 v245, 16, v195
	v_and_b32_e32 v195, 0xffff0000, v195
	v_add_f32_e32 v200, v108, v200
	v_add_f32_e32 v192, v109, v192
	v_add_f32_e32 v201, v110, v201
	v_add_f32_e32 v193, v111, v193
	v_add_f32_e32 v244, v104, v244
	v_add_f32_e32 v194, v105, v194
	v_add_f32_e32 v245, v106, v245
	v_add_f32_e32 v195, v107, v195
	v_cvt_pk_bf16_f32 v192, v200, v192
	v_cvt_pk_bf16_f32 v193, v201, v193
	v_cvt_pk_bf16_f32 v194, v244, v194
	v_cvt_pk_bf16_f32 v195, v245, v195
	global_store_dwordx4 v[158:159], v[192:195], off
	s_waitcnt vmcnt(15)
	v_lshlrev_b32_e32 v200, 16, v196
	v_and_b32_e32 v196, 0xffff0000, v196
	v_lshlrev_b32_e32 v201, 16, v197
	v_and_b32_e32 v197, 0xffff0000, v197
	v_lshlrev_b32_e32 v244, 16, v198
	v_and_b32_e32 v198, 0xffff0000, v198
	v_lshlrev_b32_e32 v245, 16, v199
	v_and_b32_e32 v199, 0xffff0000, v199
	v_add_f32_e32 v200, v100, v200
	v_add_f32_e32 v196, v101, v196
	v_add_f32_e32 v201, v102, v201
	v_add_f32_e32 v197, v103, v197
	v_add_f32_e32 v244, v96, v244
	v_add_f32_e32 v198, v97, v198
	v_add_f32_e32 v245, v98, v245
	v_add_f32_e32 v199, v99, v199
	v_cvt_pk_bf16_f32 v196, v200, v196
	v_cvt_pk_bf16_f32 v197, v201, v197
	v_cvt_pk_bf16_f32 v198, v244, v198
	v_cvt_pk_bf16_f32 v199, v245, v199
	global_store_dwordx4 v[158:159], v[196:199], off offset:256
	v_or_b32_e32 v132, 32, v130
	v_ashrrev_i32_e32 v133, 31, v132
	v_mul_lo_u32 v136, s42, v133
	v_mul_lo_u32 v131, s43, v132
	v_mad_u64_u32 v[158:159], s[8:9], s42, v132, 0
	v_add3_u32 v159, v159, v136, v131
	v_lshl_add_u64 v[158:159], v[158:159], 1, s[46:47]
	v_lshl_add_u64 v[158:159], v[158:159], 0, v[128:129]
	s_waitcnt vmcnt(15)
	v_lshlrev_b32_e32 v200, 16, v204
	v_and_b32_e32 v204, 0xffff0000, v204
	v_lshlrev_b32_e32 v201, 16, v205
	v_and_b32_e32 v205, 0xffff0000, v205
	v_lshlrev_b32_e32 v244, 16, v206
	v_and_b32_e32 v206, 0xffff0000, v206
	v_lshlrev_b32_e32 v245, 16, v207
	v_and_b32_e32 v207, 0xffff0000, v207
	v_add_f32_e32 v200, v92, v200
	v_add_f32_e32 v204, v93, v204
	v_add_f32_e32 v201, v94, v201
	v_add_f32_e32 v205, v95, v205
	v_add_f32_e32 v244, v88, v244
	v_add_f32_e32 v206, v89, v206
	v_add_f32_e32 v245, v90, v245
	v_add_f32_e32 v207, v91, v207
	v_cvt_pk_bf16_f32 v204, v200, v204
	v_cvt_pk_bf16_f32 v205, v201, v205
	v_cvt_pk_bf16_f32 v206, v244, v206
	v_cvt_pk_bf16_f32 v207, v245, v207
	global_store_dwordx4 v[158:159], v[204:207], off
	s_waitcnt vmcnt(15)
	v_lshlrev_b32_e32 v200, 16, v208
	v_and_b32_e32 v208, 0xffff0000, v208
	v_lshlrev_b32_e32 v201, 16, v209
	v_and_b32_e32 v209, 0xffff0000, v209
	v_lshlrev_b32_e32 v244, 16, v210
	v_and_b32_e32 v210, 0xffff0000, v210
	v_lshlrev_b32_e32 v245, 16, v211
	v_and_b32_e32 v211, 0xffff0000, v211
	v_add_f32_e32 v200, v84, v200
	v_add_f32_e32 v208, v85, v208
	v_add_f32_e32 v201, v86, v201
	v_add_f32_e32 v209, v87, v209
	v_add_f32_e32 v244, v80, v244
	v_add_f32_e32 v210, v81, v210
	v_add_f32_e32 v245, v82, v245
	v_add_f32_e32 v211, v83, v211
	v_cvt_pk_bf16_f32 v208, v200, v208
	v_cvt_pk_bf16_f32 v209, v201, v209
	v_cvt_pk_bf16_f32 v210, v244, v210
	v_cvt_pk_bf16_f32 v211, v245, v211
	global_store_dwordx4 v[158:159], v[208:211], off offset:256
	v_or_b32_e32 v132, 48, v130
	v_ashrrev_i32_e32 v133, 31, v132
	v_mul_lo_u32 v136, s42, v133
	v_mul_lo_u32 v131, s43, v132
	v_mad_u64_u32 v[158:159], s[8:9], s42, v132, 0
	v_add3_u32 v159, v159, v136, v131
	v_lshl_add_u64 v[158:159], v[158:159], 1, s[46:47]
	v_lshl_add_u64 v[158:159], v[158:159], 0, v[128:129]
	s_waitcnt vmcnt(15)
	v_lshlrev_b32_e32 v200, 16, v212
	v_and_b32_e32 v212, 0xffff0000, v212
	v_lshlrev_b32_e32 v201, 16, v213
	v_and_b32_e32 v213, 0xffff0000, v213
	v_lshlrev_b32_e32 v244, 16, v214
	v_and_b32_e32 v214, 0xffff0000, v214
	v_lshlrev_b32_e32 v245, 16, v215
	v_and_b32_e32 v215, 0xffff0000, v215
	v_add_f32_e32 v200, v76, v200
	v_add_f32_e32 v212, v77, v212
	v_add_f32_e32 v201, v78, v201
	v_add_f32_e32 v213, v79, v213
	v_add_f32_e32 v244, v72, v244
	v_add_f32_e32 v214, v73, v214
	v_add_f32_e32 v245, v74, v245
	v_add_f32_e32 v215, v75, v215
	v_cvt_pk_bf16_f32 v212, v200, v212
	v_cvt_pk_bf16_f32 v213, v201, v213
	v_cvt_pk_bf16_f32 v214, v244, v214
	v_cvt_pk_bf16_f32 v215, v245, v215
	global_store_dwordx4 v[158:159], v[212:215], off
	s_waitcnt vmcnt(15)
	v_lshlrev_b32_e32 v200, 16, v216
	v_and_b32_e32 v216, 0xffff0000, v216
	v_lshlrev_b32_e32 v201, 16, v217
	v_and_b32_e32 v217, 0xffff0000, v217
	v_lshlrev_b32_e32 v244, 16, v218
	v_and_b32_e32 v218, 0xffff0000, v218
	v_lshlrev_b32_e32 v245, 16, v219
	v_and_b32_e32 v219, 0xffff0000, v219
	v_add_f32_e32 v200, v68, v200
	v_add_f32_e32 v216, v69, v216
	v_add_f32_e32 v201, v70, v201
	v_add_f32_e32 v217, v71, v217
	v_add_f32_e32 v244, v64, v244
	v_add_f32_e32 v218, v65, v218
	v_add_f32_e32 v245, v66, v245
	v_add_f32_e32 v219, v67, v219
	v_cvt_pk_bf16_f32 v216, v200, v216
	v_cvt_pk_bf16_f32 v217, v201, v217
	v_cvt_pk_bf16_f32 v218, v244, v218
	v_cvt_pk_bf16_f32 v219, v245, v219
	global_store_dwordx4 v[158:159], v[216:219], off offset:256
	v_add_u32_e32 v132, s6, v164
	v_ashrrev_i32_e32 v133, 31, v132
	v_mul_lo_u32 v136, s42, v133
	v_mul_lo_u32 v131, s43, v132
	v_mad_u64_u32 v[158:159], s[8:9], s42, v132, 0
	v_add3_u32 v159, v159, v136, v131
	v_lshl_add_u64 v[158:159], v[158:159], 1, s[46:47]
	v_lshl_add_u64 v[158:159], v[158:159], 0, v[128:129]
	s_waitcnt vmcnt(15)
	v_lshlrev_b32_e32 v200, 16, v220
	v_and_b32_e32 v220, 0xffff0000, v220
	v_lshlrev_b32_e32 v201, 16, v221
	v_and_b32_e32 v221, 0xffff0000, v221
	v_lshlrev_b32_e32 v244, 16, v222
	v_and_b32_e32 v222, 0xffff0000, v222
	v_lshlrev_b32_e32 v245, 16, v223
	v_and_b32_e32 v223, 0xffff0000, v223
	v_add_f32_e32 v200, v60, v200
	v_add_f32_e32 v220, v61, v220
	v_add_f32_e32 v201, v62, v201
	v_add_f32_e32 v221, v63, v221
	v_add_f32_e32 v244, v56, v244
	v_add_f32_e32 v222, v57, v222
	v_add_f32_e32 v245, v58, v245
	v_add_f32_e32 v223, v59, v223
	v_cvt_pk_bf16_f32 v220, v200, v220
	v_cvt_pk_bf16_f32 v221, v201, v221
	v_cvt_pk_bf16_f32 v222, v244, v222
	v_cvt_pk_bf16_f32 v223, v245, v223
	global_store_dwordx4 v[158:159], v[220:223], off
	s_waitcnt vmcnt(15)
	v_lshlrev_b32_e32 v200, 16, v224
	v_and_b32_e32 v224, 0xffff0000, v224
	v_lshlrev_b32_e32 v201, 16, v225
	v_and_b32_e32 v225, 0xffff0000, v225
	v_lshlrev_b32_e32 v244, 16, v226
	v_and_b32_e32 v226, 0xffff0000, v226
	v_lshlrev_b32_e32 v245, 16, v227
	v_and_b32_e32 v227, 0xffff0000, v227
	v_add_f32_e32 v200, v52, v200
	v_add_f32_e32 v224, v53, v224
	v_add_f32_e32 v201, v54, v201
	v_add_f32_e32 v225, v55, v225
	v_add_f32_e32 v244, v48, v244
	v_add_f32_e32 v226, v49, v226
	v_add_f32_e32 v245, v50, v245
	v_add_f32_e32 v227, v51, v227
	v_cvt_pk_bf16_f32 v224, v200, v224
	v_cvt_pk_bf16_f32 v225, v201, v225
	v_cvt_pk_bf16_f32 v226, v244, v226
	v_cvt_pk_bf16_f32 v227, v245, v227
	global_store_dwordx4 v[158:159], v[224:227], off offset:256
	v_add_u32_e32 v132, s6, v165
	v_ashrrev_i32_e32 v133, 31, v132
	v_mul_lo_u32 v136, s42, v133
	v_mul_lo_u32 v131, s43, v132
	v_mad_u64_u32 v[158:159], s[8:9], s42, v132, 0
	v_add3_u32 v159, v159, v136, v131
	v_lshl_add_u64 v[158:159], v[158:159], 1, s[46:47]
	v_lshl_add_u64 v[158:159], v[158:159], 0, v[128:129]
	s_waitcnt vmcnt(15)
	v_lshlrev_b32_e32 v200, 16, v228
	v_and_b32_e32 v228, 0xffff0000, v228
	v_lshlrev_b32_e32 v201, 16, v229
	v_and_b32_e32 v229, 0xffff0000, v229
	v_lshlrev_b32_e32 v244, 16, v230
	v_and_b32_e32 v230, 0xffff0000, v230
	v_lshlrev_b32_e32 v245, 16, v231
	v_and_b32_e32 v231, 0xffff0000, v231
	v_add_f32_e32 v200, v44, v200
	v_add_f32_e32 v228, v45, v228
	v_add_f32_e32 v201, v46, v201
	v_add_f32_e32 v229, v47, v229
	v_add_f32_e32 v244, v40, v244
	v_add_f32_e32 v230, v41, v230
	v_add_f32_e32 v245, v42, v245
	v_add_f32_e32 v231, v43, v231
	v_cvt_pk_bf16_f32 v228, v200, v228
	v_cvt_pk_bf16_f32 v229, v201, v229
	v_cvt_pk_bf16_f32 v230, v244, v230
	v_cvt_pk_bf16_f32 v231, v245, v231
	global_store_dwordx4 v[158:159], v[228:231], off
	s_waitcnt vmcnt(15)
	v_lshlrev_b32_e32 v200, 16, v232
	v_and_b32_e32 v232, 0xffff0000, v232
	v_lshlrev_b32_e32 v201, 16, v233
	v_and_b32_e32 v233, 0xffff0000, v233
	v_lshlrev_b32_e32 v244, 16, v234
	v_and_b32_e32 v234, 0xffff0000, v234
	v_lshlrev_b32_e32 v245, 16, v235
	v_and_b32_e32 v235, 0xffff0000, v235
	v_add_f32_e32 v200, v36, v200
	v_add_f32_e32 v232, v37, v232
	v_add_f32_e32 v201, v38, v201
	v_add_f32_e32 v233, v39, v233
	v_add_f32_e32 v244, v32, v244
	v_add_f32_e32 v234, v33, v234
	v_add_f32_e32 v245, v34, v245
	v_add_f32_e32 v235, v35, v235
	v_cvt_pk_bf16_f32 v232, v200, v232
	v_cvt_pk_bf16_f32 v233, v201, v233
	v_cvt_pk_bf16_f32 v234, v244, v234
	v_cvt_pk_bf16_f32 v235, v245, v235
	global_store_dwordx4 v[158:159], v[232:235], off offset:256
	v_add_u32_e32 v132, s6, v166
	v_ashrrev_i32_e32 v133, 31, v132
	v_mul_lo_u32 v136, s42, v133
	v_mul_lo_u32 v131, s43, v132
	v_mad_u64_u32 v[158:159], s[8:9], s42, v132, 0
	v_add3_u32 v159, v159, v136, v131
	v_lshl_add_u64 v[158:159], v[158:159], 1, s[46:47]
	v_lshl_add_u64 v[158:159], v[158:159], 0, v[128:129]
	s_waitcnt vmcnt(15)
	v_lshlrev_b32_e32 v200, 16, v236
	v_and_b32_e32 v236, 0xffff0000, v236
	v_lshlrev_b32_e32 v201, 16, v237
	v_and_b32_e32 v237, 0xffff0000, v237
	v_lshlrev_b32_e32 v244, 16, v238
	v_and_b32_e32 v238, 0xffff0000, v238
	v_lshlrev_b32_e32 v245, 16, v239
	v_and_b32_e32 v239, 0xffff0000, v239
	v_add_f32_e32 v200, v28, v200
	v_add_f32_e32 v236, v29, v236
	v_add_f32_e32 v201, v30, v201
	v_add_f32_e32 v237, v31, v237
	v_add_f32_e32 v244, v24, v244
	v_add_f32_e32 v238, v25, v238
	v_add_f32_e32 v245, v26, v245
	v_add_f32_e32 v239, v27, v239
	v_cvt_pk_bf16_f32 v236, v200, v236
	v_cvt_pk_bf16_f32 v237, v201, v237
	v_cvt_pk_bf16_f32 v238, v244, v238
	v_cvt_pk_bf16_f32 v239, v245, v239
	global_store_dwordx4 v[158:159], v[236:239], off
	s_waitcnt vmcnt(15)
	v_lshlrev_b32_e32 v200, 16, v240
	v_and_b32_e32 v240, 0xffff0000, v240
	v_lshlrev_b32_e32 v201, 16, v241
	v_and_b32_e32 v241, 0xffff0000, v241
	v_lshlrev_b32_e32 v244, 16, v242
	v_and_b32_e32 v242, 0xffff0000, v242
	v_lshlrev_b32_e32 v245, 16, v243
	v_and_b32_e32 v243, 0xffff0000, v243
	v_add_f32_e32 v200, v20, v200
	v_add_f32_e32 v240, v21, v240
	v_add_f32_e32 v201, v22, v201
	v_add_f32_e32 v241, v23, v241
	v_add_f32_e32 v244, v16, v244
	v_add_f32_e32 v242, v17, v242
	v_add_f32_e32 v245, v18, v245
	v_add_f32_e32 v243, v19, v243
	v_cvt_pk_bf16_f32 v240, v200, v240
	v_cvt_pk_bf16_f32 v241, v201, v241
	v_cvt_pk_bf16_f32 v242, v244, v242
	v_cvt_pk_bf16_f32 v243, v245, v243
	global_store_dwordx4 v[158:159], v[240:243], off offset:256
	v_add_u32_e32 v132, s6, v167
	v_ashrrev_i32_e32 v133, 31, v132
	v_mul_lo_u32 v136, s42, v133
	v_mul_lo_u32 v131, s43, v132
	v_mad_u64_u32 v[158:159], s[8:9], s42, v132, 0
	v_add3_u32 v159, v159, v136, v131
	v_lshl_add_u64 v[158:159], v[158:159], 1, s[46:47]
	v_lshl_add_u64 v[158:159], v[158:159], 0, v[128:129]
	s_waitcnt vmcnt(15)
	v_lshlrev_b32_e32 v200, 16, v150
	v_and_b32_e32 v150, 0xffff0000, v150
	v_lshlrev_b32_e32 v201, 16, v151
	v_and_b32_e32 v151, 0xffff0000, v151
	v_lshlrev_b32_e32 v244, 16, v152
	v_and_b32_e32 v152, 0xffff0000, v152
	v_lshlrev_b32_e32 v245, 16, v153
	v_and_b32_e32 v153, 0xffff0000, v153
	v_add_f32_e32 v200, v12, v200
	v_add_f32_e32 v150, v13, v150
	v_add_f32_e32 v201, v14, v201
	v_add_f32_e32 v151, v15, v151
	v_add_f32_e32 v244, v8, v244
	v_add_f32_e32 v152, v9, v152
	v_add_f32_e32 v245, v10, v245
	v_add_f32_e32 v153, v11, v153
	v_cvt_pk_bf16_f32 v150, v200, v150
	v_cvt_pk_bf16_f32 v151, v201, v151
	v_cvt_pk_bf16_f32 v152, v244, v152
	v_cvt_pk_bf16_f32 v153, v245, v153
	global_store_dwordx4 v[158:159], v[150:153], off
	s_waitcnt vmcnt(15)
	v_lshlrev_b32_e32 v200, 16, v154
	v_and_b32_e32 v154, 0xffff0000, v154
	v_lshlrev_b32_e32 v201, 16, v155
	v_and_b32_e32 v155, 0xffff0000, v155
	v_lshlrev_b32_e32 v244, 16, v156
	v_and_b32_e32 v156, 0xffff0000, v156
	v_lshlrev_b32_e32 v245, 16, v157
	v_and_b32_e32 v157, 0xffff0000, v157
	v_add_f32_e32 v200, v4, v200
	v_add_f32_e32 v154, v5, v154
	v_add_f32_e32 v201, v6, v201
	v_add_f32_e32 v155, v7, v155
	v_add_f32_e32 v244, v0, v244
	v_add_f32_e32 v156, v1, v156
	v_add_f32_e32 v245, v2, v245
	v_add_f32_e32 v157, v3, v157
	v_cvt_pk_bf16_f32 v154, v200, v154
	v_cvt_pk_bf16_f32 v155, v201, v155
	v_cvt_pk_bf16_f32 v156, v244, v156
	v_cvt_pk_bf16_f32 v157, v245, v157
	global_store_dwordx4 v[158:159], v[154:157], off offset:256
	s_mov_b64 s[6:7], 0

.LBB0_1632:
	s_andn2_b64 vcc, exec, s[6:7]
	s_cbranch_vccnz .LBB0_1634
	s_lshl_b32 s6, s83, 8
	v_readlane_b32 s8, v253, 2
	v_readlane_b32 s9, v253, 3
	v_add_u32_e32 v130, s6, v161
	v_lshl_or_b32 v128, s82, 8, v168
	v_ashrrev_i32_e32 v129, 31, v128
	v_lshlrev_b64 v[128:129], 1, v[128:129]
	v_mov_b32_e32 v132, v130
	v_ashrrev_i32_e32 v133, 31, v132
	v_lshlrev_b64 v[134:135], 12, v[132:133]
	v_lshl_add_u64 v[134:135], s[8:9], 0, v[134:135]
	v_lshl_add_u64 v[134:135], v[134:135], 0, s[58:59]
	v_lshl_add_u64 v[134:135], v[134:135], 0, v[128:129]
	global_load_dwordx4 v[170:173], v[134:135], off
	v_lshlrev_b64 v[134:135], 11, v[132:133]
	v_lshl_add_u64 v[134:135], s[46:47], 0, v[134:135]
	v_lshl_add_u64 v[134:135], v[134:135], 0, v[128:129]
	global_load_dwordx4 v[220:223], v[134:135], off
	v_mov_b32_e32 v132, v130
	v_ashrrev_i32_e32 v133, 31, v132
	v_lshlrev_b64 v[134:135], 12, v[132:133]
	v_lshl_add_u64 v[134:135], s[8:9], 0, v[134:135]
	v_lshl_add_u64 v[134:135], v[134:135], 0, s[58:59]
	v_lshl_add_u64 v[134:135], v[134:135], 0, v[128:129]
	global_load_dwordx4 v[188:191], v[134:135], off offset:256
	v_lshlrev_b64 v[134:135], 11, v[132:133]
	v_lshl_add_u64 v[134:135], s[46:47], 0, v[134:135]
	v_lshl_add_u64 v[134:135], v[134:135], 0, v[128:129]
	global_load_dwordx4 v[224:227], v[134:135], off offset:256
	v_or_b32_e32 v132, 16, v130
	v_ashrrev_i32_e32 v133, 31, v132
	v_lshlrev_b64 v[134:135], 12, v[132:133]
	v_lshl_add_u64 v[134:135], s[8:9], 0, v[134:135]
	v_lshl_add_u64 v[134:135], v[134:135], 0, s[58:59]
	v_lshl_add_u64 v[134:135], v[134:135], 0, v[128:129]
	global_load_dwordx4 v[192:195], v[134:135], off
	v_lshlrev_b64 v[134:135], 11, v[132:133]
	v_lshl_add_u64 v[134:135], s[46:47], 0, v[134:135]
	v_lshl_add_u64 v[134:135], v[134:135], 0, v[128:129]
	global_load_dwordx4 v[228:231], v[134:135], off
	v_or_b32_e32 v132, 16, v130
	v_ashrrev_i32_e32 v133, 31, v132
	v_lshlrev_b64 v[134:135], 12, v[132:133]
	v_lshl_add_u64 v[134:135], s[8:9], 0, v[134:135]
	v_lshl_add_u64 v[134:135], v[134:135], 0, s[58:59]
	v_lshl_add_u64 v[134:135], v[134:135], 0, v[128:129]
	global_load_dwordx4 v[196:199], v[134:135], off offset:256
	v_lshlrev_b64 v[134:135], 11, v[132:133]
	v_lshl_add_u64 v[134:135], s[46:47], 0, v[134:135]
	v_lshl_add_u64 v[134:135], v[134:135], 0, v[128:129]
	global_load_dwordx4 v[232:235], v[134:135], off offset:256
	v_or_b32_e32 v132, 32, v130
	v_ashrrev_i32_e32 v133, 31, v132
	v_lshlrev_b64 v[134:135], 12, v[132:133]
	v_lshl_add_u64 v[134:135], s[8:9], 0, v[134:135]
	v_lshl_add_u64 v[134:135], v[134:135], 0, s[58:59]
	v_lshl_add_u64 v[134:135], v[134:135], 0, v[128:129]
	global_load_dwordx4 v[204:207], v[134:135], off
	v_lshlrev_b64 v[134:135], 11, v[132:133]
	v_lshl_add_u64 v[134:135], s[46:47], 0, v[134:135]
	v_lshl_add_u64 v[134:135], v[134:135], 0, v[128:129]
	global_load_dwordx4 v[236:239], v[134:135], off
	v_or_b32_e32 v132, 32, v130
	v_ashrrev_i32_e32 v133, 31, v132
	v_lshlrev_b64 v[134:135], 12, v[132:133]
	v_lshl_add_u64 v[134:135], s[8:9], 0, v[134:135]
	v_lshl_add_u64 v[134:135], v[134:135], 0, s[58:59]
	v_lshl_add_u64 v[134:135], v[134:135], 0, v[128:129]
	global_load_dwordx4 v[208:211], v[134:135], off offset:256
	v_lshlrev_b64 v[134:135], 11, v[132:133]
	v_lshl_add_u64 v[134:135], s[46:47], 0, v[134:135]
	v_lshl_add_u64 v[134:135], v[134:135], 0, v[128:129]
	global_load_dwordx4 v[240:243], v[134:135], off offset:256
	v_or_b32_e32 v132, 48, v130
	v_ashrrev_i32_e32 v133, 31, v132
	v_lshlrev_b64 v[134:135], 12, v[132:133]
	v_lshl_add_u64 v[134:135], s[8:9], 0, v[134:135]
	v_lshl_add_u64 v[134:135], v[134:135], 0, s[58:59]
	v_lshl_add_u64 v[134:135], v[134:135], 0, v[128:129]
	global_load_dwordx4 v[212:215], v[134:135], off
	v_lshlrev_b64 v[134:135], 11, v[132:133]
	v_lshl_add_u64 v[134:135], s[46:47], 0, v[134:135]
	v_lshl_add_u64 v[134:135], v[134:135], 0, v[128:129]
	global_load_dwordx4 v[150:153], v[134:135], off
	v_or_b32_e32 v132, 48, v130
	v_ashrrev_i32_e32 v133, 31, v132
	v_lshlrev_b64 v[134:135], 12, v[132:133]
	v_lshl_add_u64 v[134:135], s[8:9], 0, v[134:135]
	v_lshl_add_u64 v[134:135], v[134:135], 0, s[58:59]
	v_lshl_add_u64 v[134:135], v[134:135], 0, v[128:129]
	global_load_dwordx4 v[216:219], v[134:135], off offset:256
	v_lshlrev_b64 v[134:135], 11, v[132:133]
	v_lshl_add_u64 v[134:135], s[46:47], 0, v[134:135]
	v_lshl_add_u64 v[134:135], v[134:135], 0, v[128:129]
	global_load_dwordx4 v[154:157], v[134:135], off offset:256
	v_mov_b32_e32 v132, v130
	v_ashrrev_i32_e32 v133, 31, v132
	v_lshlrev_b64 v[158:159], 11, v[132:133]
	v_lshl_add_u64 v[158:159], s[46:47], 0, v[158:159]
	v_lshl_add_u64 v[158:159], v[158:159], 0, v[128:129]
	s_waitcnt vmcnt(14)
	v_lshlrev_b32_e32 v200, 16, v220
	v_lshlrev_b32_e32 v136, 16, v170
	v_fmac_f32_e32 v200, v124, v136
	v_and_b32_e32 v220, 0xffff0000, v220
	v_and_b32_e32 v170, 0xffff0000, v170
	v_fmac_f32_e32 v220, v125, v170
	v_lshlrev_b32_e32 v201, 16, v221
	v_lshlrev_b32_e32 v136, 16, v171
	v_fmac_f32_e32 v201, v126, v136
	v_and_b32_e32 v221, 0xffff0000, v221
	v_and_b32_e32 v171, 0xffff0000, v171
	v_fmac_f32_e32 v221, v127, v171
	v_lshlrev_b32_e32 v244, 16, v222
	v_lshlrev_b32_e32 v136, 16, v172
	v_fmac_f32_e32 v244, v120, v136
	v_and_b32_e32 v222, 0xffff0000, v222
	v_and_b32_e32 v172, 0xffff0000, v172
	v_fmac_f32_e32 v222, v121, v172
	v_lshlrev_b32_e32 v245, 16, v223
	v_lshlrev_b32_e32 v136, 16, v173
	v_fmac_f32_e32 v245, v122, v136
	v_and_b32_e32 v223, 0xffff0000, v223
	v_and_b32_e32 v173, 0xffff0000, v173
	v_fmac_f32_e32 v223, v123, v173
	v_cvt_pk_bf16_f32 v220, v200, v220
	v_cvt_pk_bf16_f32 v221, v201, v221
	v_cvt_pk_bf16_f32 v222, v244, v222
	v_cvt_pk_bf16_f32 v223, v245, v223
	global_store_dwordx4 v[158:159], v[220:223], off
	v_add_u32_e32 v132, s6, v164
	v_ashrrev_i32_e32 v133, 31, v132
	v_lshlrev_b64 v[134:135], 12, v[132:133]
	v_lshl_add_u64 v[134:135], s[8:9], 0, v[134:135]
	v_lshl_add_u64 v[134:135], v[134:135], 0, s[58:59]
	v_lshl_add_u64 v[134:135], v[134:135], 0, v[128:129]
	global_load_dwordx4 v[170:173], v[134:135], off
	v_lshlrev_b64 v[134:135], 11, v[132:133]
	v_lshl_add_u64 v[134:135], s[46:47], 0, v[134:135]
	v_lshl_add_u64 v[134:135], v[134:135], 0, v[128:129]
	global_load_dwordx4 v[220:223], v[134:135], off
	v_mov_b32_e32 v132, v130
	v_ashrrev_i32_e32 v133, 31, v132
	v_lshlrev_b64 v[158:159], 11, v[132:133]
	v_lshl_add_u64 v[158:159], s[46:47], 0, v[158:159]
	v_lshl_add_u64 v[158:159], v[158:159], 0, v[128:129]
	s_waitcnt vmcnt(15)
	v_lshlrev_b32_e32 v200, 16, v224
	v_lshlrev_b32_e32 v136, 16, v188
	v_fmac_f32_e32 v200, v116, v136
	v_and_b32_e32 v224, 0xffff0000, v224
	v_and_b32_e32 v188, 0xffff0000, v188
	v_fmac_f32_e32 v224, v117, v188
	v_lshlrev_b32_e32 v201, 16, v225
	v_lshlrev_b32_e32 v136, 16, v189
	v_fmac_f32_e32 v201, v118, v136
	v_and_b32_e32 v225, 0xffff0000, v225
	v_and_b32_e32 v189, 0xffff0000, v189
	v_fmac_f32_e32 v225, v119, v189
	v_lshlrev_b32_e32 v244, 16, v226
	v_lshlrev_b32_e32 v136, 16, v190
	v_fmac_f32_e32 v244, v112, v136
	v_and_b32_e32 v226, 0xffff0000, v226
	v_and_b32_e32 v190, 0xffff0000, v190
	v_fmac_f32_e32 v226, v113, v190
	v_lshlrev_b32_e32 v245, 16, v227
	v_lshlrev_b32_e32 v136, 16, v191
	v_fmac_f32_e32 v245, v114, v136
	v_and_b32_e32 v227, 0xffff0000, v227
	v_and_b32_e32 v191, 0xffff0000, v191
	v_fmac_f32_e32 v227, v115, v191
	v_cvt_pk_bf16_f32 v224, v200, v224
	v_cvt_pk_bf16_f32 v225, v201, v225
	v_cvt_pk_bf16_f32 v226, v244, v226
	v_cvt_pk_bf16_f32 v227, v245, v227
	global_store_dwordx4 v[158:159], v[224:227], off offset:256
	v_add_u32_e32 v132, s6, v164
	v_ashrrev_i32_e32 v133, 31, v132
	v_lshlrev_b64 v[134:135], 12, v[132:133]
	v_lshl_add_u64 v[134:135], s[8:9], 0, v[134:135]
	v_lshl_add_u64 v[134:135], v[134:135], 0, s[58:59]
	v_lshl_add_u64 v[134:135], v[134:135], 0, v[128:129]
	global_load_dwordx4 v[188:191], v[134:135], off offset:256
	v_lshlrev_b64 v[134:135], 11, v[132:133]
	v_lshl_add_u64 v[134:135], s[46:47], 0, v[134:135]
	v_lshl_add_u64 v[134:135], v[134:135], 0, v[128:129]
	global_load_dwordx4 v[224:227], v[134:135], off offset:256
	v_or_b32_e32 v132, 16, v130
	v_ashrrev_i32_e32 v133, 31, v132
	v_lshlrev_b64 v[158:159], 11, v[132:133]
	v_lshl_add_u64 v[158:159], s[46:47], 0, v[158:159]
	v_lshl_add_u64 v[158:159], v[158:159], 0, v[128:129]
	s_waitcnt vmcnt(16)
	v_lshlrev_b32_e32 v200, 16, v228
	v_lshlrev_b32_e32 v136, 16, v192
	v_fmac_f32_e32 v200, v108, v136
	v_and_b32_e32 v228, 0xffff0000, v228
	v_and_b32_e32 v192, 0xffff0000, v192
	v_fmac_f32_e32 v228, v109, v192
	v_lshlrev_b32_e32 v201, 16, v229
	v_lshlrev_b32_e32 v136, 16, v193
	v_fmac_f32_e32 v201, v110, v136
	v_and_b32_e32 v229, 0xffff0000, v229
	v_and_b32_e32 v193, 0xffff0000, v193
	v_fmac_f32_e32 v229, v111, v193
	v_lshlrev_b32_e32 v244, 16, v230
	v_lshlrev_b32_e32 v136, 16, v194
	v_fmac_f32_e32 v244, v104, v136
	v_and_b32_e32 v230, 0xffff0000, v230
	v_and_b32_e32 v194, 0xffff0000, v194
	v_fmac_f32_e32 v230, v105, v194
	v_lshlrev_b32_e32 v245, 16, v231
	v_lshlrev_b32_e32 v136, 16, v195
	v_fmac_f32_e32 v245, v106, v136
	v_and_b32_e32 v231, 0xffff0000, v231
	v_and_b32_e32 v195, 0xffff0000, v195
	v_fmac_f32_e32 v231, v107, v195
	v_cvt_pk_bf16_f32 v228, v200, v228
	v_cvt_pk_bf16_f32 v229, v201, v229
	v_cvt_pk_bf16_f32 v230, v244, v230
	v_cvt_pk_bf16_f32 v231, v245, v231
	global_store_dwordx4 v[158:159], v[228:231], off
	v_add_u32_e32 v132, s6, v165
	v_ashrrev_i32_e32 v133, 31, v132
	v_lshlrev_b64 v[134:135], 12, v[132:133]
	v_lshl_add_u64 v[134:135], s[8:9], 0, v[134:135]
	v_lshl_add_u64 v[134:135], v[134:135], 0, s[58:59]
	v_lshl_add_u64 v[134:135], v[134:135], 0, v[128:129]
	global_load_dwordx4 v[192:195], v[134:135], off
	v_lshlrev_b64 v[134:135], 11, v[132:133]
	v_lshl_add_u64 v[134:135], s[46:47], 0, v[134:135]
	v_lshl_add_u64 v[134:135], v[134:135], 0, v[128:129]
	global_load_dwordx4 v[228:231], v[134:135], off
	v_or_b32_e32 v132, 16, v130
	v_ashrrev_i32_e32 v133, 31, v132
	v_lshlrev_b64 v[158:159], 11, v[132:133]
	v_lshl_add_u64 v[158:159], s[46:47], 0, v[158:159]
	v_lshl_add_u64 v[158:159], v[158:159], 0, v[128:129]
	s_waitcnt vmcnt(17)
	v_lshlrev_b32_e32 v200, 16, v232
	v_lshlrev_b32_e32 v136, 16, v196
	v_fmac_f32_e32 v200, v100, v136
	v_and_b32_e32 v232, 0xffff0000, v232
	v_and_b32_e32 v196, 0xffff0000, v196
	v_fmac_f32_e32 v232, v101, v196
	v_lshlrev_b32_e32 v201, 16, v233
	v_lshlrev_b32_e32 v136, 16, v197
	v_fmac_f32_e32 v201, v102, v136
	v_and_b32_e32 v233, 0xffff0000, v233
	v_and_b32_e32 v197, 0xffff0000, v197
	v_fmac_f32_e32 v233, v103, v197
	v_lshlrev_b32_e32 v244, 16, v234
	v_lshlrev_b32_e32 v136, 16, v198
	v_fmac_f32_e32 v244, v96, v136
	v_and_b32_e32 v234, 0xffff0000, v234
	v_and_b32_e32 v198, 0xffff0000, v198
	v_fmac_f32_e32 v234, v97, v198
	v_lshlrev_b32_e32 v245, 16, v235
	v_lshlrev_b32_e32 v136, 16, v199
	v_fmac_f32_e32 v245, v98, v136
	v_and_b32_e32 v235, 0xffff0000, v235
	v_and_b32_e32 v199, 0xffff0000, v199
	v_fmac_f32_e32 v235, v99, v199
	v_cvt_pk_bf16_f32 v232, v200, v232
	v_cvt_pk_bf16_f32 v233, v201, v233
	v_cvt_pk_bf16_f32 v234, v244, v234
	v_cvt_pk_bf16_f32 v235, v245, v235
	global_store_dwordx4 v[158:159], v[232:235], off offset:256
	v_add_u32_e32 v132, s6, v165
	v_ashrrev_i32_e32 v133, 31, v132
	v_lshlrev_b64 v[134:135], 12, v[132:133]
	v_lshl_add_u64 v[134:135], s[8:9], 0, v[134:135]
	v_lshl_add_u64 v[134:135], v[134:135], 0, s[58:59]
	v_lshl_add_u64 v[134:135], v[134:135], 0, v[128:129]
	global_load_dwordx4 v[196:199], v[134:135], off offset:256
	v_lshlrev_b64 v[134:135], 11, v[132:133]
	v_lshl_add_u64 v[134:135], s[46:47], 0, v[134:135]
	v_lshl_add_u64 v[134:135], v[134:135], 0, v[128:129]
	global_load_dwordx4 v[232:235], v[134:135], off offset:256
	v_or_b32_e32 v132, 32, v130
	v_ashrrev_i32_e32 v133, 31, v132
	v_lshlrev_b64 v[158:159], 11, v[132:133]
	v_lshl_add_u64 v[158:159], s[46:47], 0, v[158:159]
	v_lshl_add_u64 v[158:159], v[158:159], 0, v[128:129]
	s_waitcnt vmcnt(18)
	v_lshlrev_b32_e32 v200, 16, v236
	v_lshlrev_b32_e32 v136, 16, v204
	v_fmac_f32_e32 v200, v92, v136
	v_and_b32_e32 v236, 0xffff0000, v236
	v_and_b32_e32 v204, 0xffff0000, v204
	v_fmac_f32_e32 v236, v93, v204
	v_lshlrev_b32_e32 v201, 16, v237
	v_lshlrev_b32_e32 v136, 16, v205
	v_fmac_f32_e32 v201, v94, v136
	v_and_b32_e32 v237, 0xffff0000, v237
	v_and_b32_e32 v205, 0xffff0000, v205
	v_fmac_f32_e32 v237, v95, v205
	v_lshlrev_b32_e32 v244, 16, v238
	v_lshlrev_b32_e32 v136, 16, v206
	v_fmac_f32_e32 v244, v88, v136
	v_and_b32_e32 v238, 0xffff0000, v238
	v_and_b32_e32 v206, 0xffff0000, v206
	v_fmac_f32_e32 v238, v89, v206
	v_lshlrev_b32_e32 v245, 16, v239
	v_lshlrev_b32_e32 v136, 16, v207
	v_fmac_f32_e32 v245, v90, v136
	v_and_b32_e32 v239, 0xffff0000, v239
	v_and_b32_e32 v207, 0xffff0000, v207
	v_fmac_f32_e32 v239, v91, v207
	v_cvt_pk_bf16_f32 v236, v200, v236
	v_cvt_pk_bf16_f32 v237, v201, v237
	v_cvt_pk_bf16_f32 v238, v244, v238
	v_cvt_pk_bf16_f32 v239, v245, v239
	global_store_dwordx4 v[158:159], v[236:239], off
	v_add_u32_e32 v132, s6, v166
	v_ashrrev_i32_e32 v133, 31, v132
	v_lshlrev_b64 v[134:135], 12, v[132:133]
	v_lshl_add_u64 v[134:135], s[8:9], 0, v[134:135]
	v_lshl_add_u64 v[134:135], v[134:135], 0, s[58:59]
	v_lshl_add_u64 v[134:135], v[134:135], 0, v[128:129]
	global_load_dwordx4 v[204:207], v[134:135], off
	v_lshlrev_b64 v[134:135], 11, v[132:133]
	v_lshl_add_u64 v[134:135], s[46:47], 0, v[134:135]
	v_lshl_add_u64 v[134:135], v[134:135], 0, v[128:129]
	global_load_dwordx4 v[236:239], v[134:135], off
	v_or_b32_e32 v132, 32, v130
	v_ashrrev_i32_e32 v133, 31, v132
	v_lshlrev_b64 v[158:159], 11, v[132:133]
	v_lshl_add_u64 v[158:159], s[46:47], 0, v[158:159]
	v_lshl_add_u64 v[158:159], v[158:159], 0, v[128:129]
	s_waitcnt vmcnt(19)
	v_lshlrev_b32_e32 v200, 16, v240
	v_lshlrev_b32_e32 v136, 16, v208
	v_fmac_f32_e32 v200, v84, v136
	v_and_b32_e32 v240, 0xffff0000, v240
	v_and_b32_e32 v208, 0xffff0000, v208
	v_fmac_f32_e32 v240, v85, v208
	v_lshlrev_b32_e32 v201, 16, v241
	v_lshlrev_b32_e32 v136, 16, v209
	v_fmac_f32_e32 v201, v86, v136
	v_and_b32_e32 v241, 0xffff0000, v241
	v_and_b32_e32 v209, 0xffff0000, v209
	v_fmac_f32_e32 v241, v87, v209
	v_lshlrev_b32_e32 v244, 16, v242
	v_lshlrev_b32_e32 v136, 16, v210
	v_fmac_f32_e32 v244, v80, v136
	v_and_b32_e32 v242, 0xffff0000, v242
	v_and_b32_e32 v210, 0xffff0000, v210
	v_fmac_f32_e32 v242, v81, v210
	v_lshlrev_b32_e32 v245, 16, v243
	v_lshlrev_b32_e32 v136, 16, v211
	v_fmac_f32_e32 v245, v82, v136
	v_and_b32_e32 v243, 0xffff0000, v243
	v_and_b32_e32 v211, 0xffff0000, v211
	v_fmac_f32_e32 v243, v83, v211
	v_cvt_pk_bf16_f32 v240, v200, v240
	v_cvt_pk_bf16_f32 v241, v201, v241
	v_cvt_pk_bf16_f32 v242, v244, v242
	v_cvt_pk_bf16_f32 v243, v245, v243
	global_store_dwordx4 v[158:159], v[240:243], off offset:256
	v_add_u32_e32 v132, s6, v166
	v_ashrrev_i32_e32 v133, 31, v132
	v_lshlrev_b64 v[134:135], 12, v[132:133]
	v_lshl_add_u64 v[134:135], s[8:9], 0, v[134:135]
	v_lshl_add_u64 v[134:135], v[134:135], 0, s[58:59]
	v_lshl_add_u64 v[134:135], v[134:135], 0, v[128:129]
	global_load_dwordx4 v[208:211], v[134:135], off offset:256
	v_lshlrev_b64 v[134:135], 11, v[132:133]
	v_lshl_add_u64 v[134:135], s[46:47], 0, v[134:135]
	v_lshl_add_u64 v[134:135], v[134:135], 0, v[128:129]
	global_load_dwordx4 v[240:243], v[134:135], off offset:256
	v_or_b32_e32 v132, 48, v130
	v_ashrrev_i32_e32 v133, 31, v132
	v_lshlrev_b64 v[158:159], 11, v[132:133]
	v_lshl_add_u64 v[158:159], s[46:47], 0, v[158:159]
	v_lshl_add_u64 v[158:159], v[158:159], 0, v[128:129]
	s_waitcnt vmcnt(20)
	v_lshlrev_b32_e32 v200, 16, v150
	v_lshlrev_b32_e32 v136, 16, v212
	v_fmac_f32_e32 v200, v76, v136
	v_and_b32_e32 v150, 0xffff0000, v150
	v_and_b32_e32 v212, 0xffff0000, v212
	v_fmac_f32_e32 v150, v77, v212
	v_lshlrev_b32_e32 v201, 16, v151
	v_lshlrev_b32_e32 v136, 16, v213
	v_fmac_f32_e32 v201, v78, v136
	v_and_b32_e32 v151, 0xffff0000, v151
	v_and_b32_e32 v213, 0xffff0000, v213
	v_fmac_f32_e32 v151, v79, v213
	v_lshlrev_b32_e32 v244, 16, v152
	v_lshlrev_b32_e32 v136, 16, v214
	v_fmac_f32_e32 v244, v72, v136
	v_and_b32_e32 v152, 0xffff0000, v152
	v_and_b32_e32 v214, 0xffff0000, v214
	v_fmac_f32_e32 v152, v73, v214
	v_lshlrev_b32_e32 v245, 16, v153
	v_lshlrev_b32_e32 v136, 16, v215
	v_fmac_f32_e32 v245, v74, v136
	v_and_b32_e32 v153, 0xffff0000, v153
	v_and_b32_e32 v215, 0xffff0000, v215
	v_fmac_f32_e32 v153, v75, v215
	v_cvt_pk_bf16_f32 v150, v200, v150
	v_cvt_pk_bf16_f32 v151, v201, v151
	v_cvt_pk_bf16_f32 v152, v244, v152
	v_cvt_pk_bf16_f32 v153, v245, v153
	global_store_dwordx4 v[158:159], v[150:153], off
	v_add_u32_e32 v132, s6, v167
	v_ashrrev_i32_e32 v133, 31, v132
	v_lshlrev_b64 v[134:135], 12, v[132:133]
	v_lshl_add_u64 v[134:135], s[8:9], 0, v[134:135]
	v_lshl_add_u64 v[134:135], v[134:135], 0, s[58:59]
	v_lshl_add_u64 v[134:135], v[134:135], 0, v[128:129]
	global_load_dwordx4 v[212:215], v[134:135], off
	v_lshlrev_b64 v[134:135], 11, v[132:133]
	v_lshl_add_u64 v[134:135], s[46:47], 0, v[134:135]
	v_lshl_add_u64 v[134:135], v[134:135], 0, v[128:129]
	global_load_dwordx4 v[150:153], v[134:135], off
	v_or_b32_e32 v132, 48, v130
	v_ashrrev_i32_e32 v133, 31, v132
	v_lshlrev_b64 v[158:159], 11, v[132:133]
	v_lshl_add_u64 v[158:159], s[46:47], 0, v[158:159]
	v_lshl_add_u64 v[158:159], v[158:159], 0, v[128:129]
	s_waitcnt vmcnt(21)
	v_lshlrev_b32_e32 v200, 16, v154
	v_lshlrev_b32_e32 v136, 16, v216
	v_fmac_f32_e32 v200, v68, v136
	v_and_b32_e32 v154, 0xffff0000, v154
	v_and_b32_e32 v216, 0xffff0000, v216
	v_fmac_f32_e32 v154, v69, v216
	v_lshlrev_b32_e32 v201, 16, v155
	v_lshlrev_b32_e32 v136, 16, v217
	v_fmac_f32_e32 v201, v70, v136
	v_and_b32_e32 v155, 0xffff0000, v155
	v_and_b32_e32 v217, 0xffff0000, v217
	v_fmac_f32_e32 v155, v71, v217
	v_lshlrev_b32_e32 v244, 16, v156
	v_lshlrev_b32_e32 v136, 16, v218
	v_fmac_f32_e32 v244, v64, v136
	v_and_b32_e32 v156, 0xffff0000, v156
	v_and_b32_e32 v218, 0xffff0000, v218
	v_fmac_f32_e32 v156, v65, v218
	v_lshlrev_b32_e32 v245, 16, v157
	v_lshlrev_b32_e32 v136, 16, v219
	v_fmac_f32_e32 v245, v66, v136
	v_and_b32_e32 v157, 0xffff0000, v157
	v_and_b32_e32 v219, 0xffff0000, v219
	v_fmac_f32_e32 v157, v67, v219
	v_cvt_pk_bf16_f32 v154, v200, v154
	v_cvt_pk_bf16_f32 v155, v201, v155
	v_cvt_pk_bf16_f32 v156, v244, v156
	v_cvt_pk_bf16_f32 v157, v245, v157
	global_store_dwordx4 v[158:159], v[154:157], off offset:256
	v_add_u32_e32 v132, s6, v167
	v_ashrrev_i32_e32 v133, 31, v132
	v_lshlrev_b64 v[134:135], 12, v[132:133]
	v_lshl_add_u64 v[134:135], s[8:9], 0, v[134:135]
	v_lshl_add_u64 v[134:135], v[134:135], 0, s[58:59]
	v_lshl_add_u64 v[134:135], v[134:135], 0, v[128:129]
	global_load_dwordx4 v[216:219], v[134:135], off offset:256
	v_lshlrev_b64 v[134:135], 11, v[132:133]
	v_lshl_add_u64 v[134:135], s[46:47], 0, v[134:135]
	v_lshl_add_u64 v[134:135], v[134:135], 0, v[128:129]
	global_load_dwordx4 v[154:157], v[134:135], off offset:256
	v_add_u32_e32 v132, s6, v164
	v_ashrrev_i32_e32 v133, 31, v132
	v_lshlrev_b64 v[158:159], 11, v[132:133]
	v_lshl_add_u64 v[158:159], s[46:47], 0, v[158:159]
	v_lshl_add_u64 v[158:159], v[158:159], 0, v[128:129]
	s_waitcnt vmcnt(21)
	v_lshlrev_b32_e32 v200, 16, v220
	v_lshlrev_b32_e32 v136, 16, v170
	v_fmac_f32_e32 v200, v60, v136
	v_and_b32_e32 v220, 0xffff0000, v220
	v_and_b32_e32 v170, 0xffff0000, v170
	v_fmac_f32_e32 v220, v61, v170
	v_lshlrev_b32_e32 v201, 16, v221
	v_lshlrev_b32_e32 v136, 16, v171
	v_fmac_f32_e32 v201, v62, v136
	v_and_b32_e32 v221, 0xffff0000, v221
	v_and_b32_e32 v171, 0xffff0000, v171
	v_fmac_f32_e32 v221, v63, v171
	v_lshlrev_b32_e32 v244, 16, v222
	v_lshlrev_b32_e32 v136, 16, v172
	v_fmac_f32_e32 v244, v56, v136
	v_and_b32_e32 v222, 0xffff0000, v222
	v_and_b32_e32 v172, 0xffff0000, v172
	v_fmac_f32_e32 v222, v57, v172
	v_lshlrev_b32_e32 v245, 16, v223
	v_lshlrev_b32_e32 v136, 16, v173
	v_fmac_f32_e32 v245, v58, v136
	v_and_b32_e32 v223, 0xffff0000, v223
	v_and_b32_e32 v173, 0xffff0000, v173
	v_fmac_f32_e32 v223, v59, v173
	v_cvt_pk_bf16_f32 v220, v200, v220
	v_cvt_pk_bf16_f32 v221, v201, v221
	v_cvt_pk_bf16_f32 v222, v244, v222
	v_cvt_pk_bf16_f32 v223, v245, v223
	global_store_dwordx4 v[158:159], v[220:223], off
	v_add_u32_e32 v132, s6, v164
	v_ashrrev_i32_e32 v133, 31, v132
	v_lshlrev_b64 v[158:159], 11, v[132:133]
	v_lshl_add_u64 v[158:159], s[46:47], 0, v[158:159]
	v_lshl_add_u64 v[158:159], v[158:159], 0, v[128:129]
	s_waitcnt vmcnt(19)
	v_lshlrev_b32_e32 v200, 16, v224
	v_lshlrev_b32_e32 v136, 16, v188
	v_fmac_f32_e32 v200, v52, v136
	v_and_b32_e32 v224, 0xffff0000, v224
	v_and_b32_e32 v188, 0xffff0000, v188
	v_fmac_f32_e32 v224, v53, v188
	v_lshlrev_b32_e32 v201, 16, v225
	v_lshlrev_b32_e32 v136, 16, v189
	v_fmac_f32_e32 v201, v54, v136
	v_and_b32_e32 v225, 0xffff0000, v225
	v_and_b32_e32 v189, 0xffff0000, v189
	v_fmac_f32_e32 v225, v55, v189
	v_lshlrev_b32_e32 v244, 16, v226
	v_lshlrev_b32_e32 v136, 16, v190
	v_fmac_f32_e32 v244, v48, v136
	v_and_b32_e32 v226, 0xffff0000, v226
	v_and_b32_e32 v190, 0xffff0000, v190
	v_fmac_f32_e32 v226, v49, v190
	v_lshlrev_b32_e32 v245, 16, v227
	v_lshlrev_b32_e32 v136, 16, v191
	v_fmac_f32_e32 v245, v50, v136
	v_and_b32_e32 v227, 0xffff0000, v227
	v_and_b32_e32 v191, 0xffff0000, v191
	v_fmac_f32_e32 v227, v51, v191
	v_cvt_pk_bf16_f32 v224, v200, v224
	v_cvt_pk_bf16_f32 v225, v201, v225
	v_cvt_pk_bf16_f32 v226, v244, v226
	v_cvt_pk_bf16_f32 v227, v245, v227
	global_store_dwordx4 v[158:159], v[224:227], off offset:256
	v_add_u32_e32 v132, s6, v165
	v_ashrrev_i32_e32 v133, 31, v132
	v_lshlrev_b64 v[158:159], 11, v[132:133]
	v_lshl_add_u64 v[158:159], s[46:47], 0, v[158:159]
	v_lshl_add_u64 v[158:159], v[158:159], 0, v[128:129]
	s_waitcnt vmcnt(17)
	v_lshlrev_b32_e32 v200, 16, v228
	v_lshlrev_b32_e32 v136, 16, v192
	v_fmac_f32_e32 v200, v44, v136
	v_and_b32_e32 v228, 0xffff0000, v228
	v_and_b32_e32 v192, 0xffff0000, v192
	v_fmac_f32_e32 v228, v45, v192
	v_lshlrev_b32_e32 v201, 16, v229
	v_lshlrev_b32_e32 v136, 16, v193
	v_fmac_f32_e32 v201, v46, v136
	v_and_b32_e32 v229, 0xffff0000, v229
	v_and_b32_e32 v193, 0xffff0000, v193
	v_fmac_f32_e32 v229, v47, v193
	v_lshlrev_b32_e32 v244, 16, v230
	v_lshlrev_b32_e32 v136, 16, v194
	v_fmac_f32_e32 v244, v40, v136
	v_and_b32_e32 v230, 0xffff0000, v230
	v_and_b32_e32 v194, 0xffff0000, v194
	v_fmac_f32_e32 v230, v41, v194
	v_lshlrev_b32_e32 v245, 16, v231
	v_lshlrev_b32_e32 v136, 16, v195
	v_fmac_f32_e32 v245, v42, v136
	v_and_b32_e32 v231, 0xffff0000, v231
	v_and_b32_e32 v195, 0xffff0000, v195
	v_fmac_f32_e32 v231, v43, v195
	v_cvt_pk_bf16_f32 v228, v200, v228
	v_cvt_pk_bf16_f32 v229, v201, v229
	v_cvt_pk_bf16_f32 v230, v244, v230
	v_cvt_pk_bf16_f32 v231, v245, v231
	global_store_dwordx4 v[158:159], v[228:231], off
	v_add_u32_e32 v132, s6, v165
	v_ashrrev_i32_e32 v133, 31, v132
	v_lshlrev_b64 v[158:159], 11, v[132:133]
	v_lshl_add_u64 v[158:159], s[46:47], 0, v[158:159]
	v_lshl_add_u64 v[158:159], v[158:159], 0, v[128:129]
	s_waitcnt vmcnt(15)
	v_lshlrev_b32_e32 v200, 16, v232
	v_lshlrev_b32_e32 v136, 16, v196
	v_fmac_f32_e32 v200, v36, v136
	v_and_b32_e32 v232, 0xffff0000, v232
	v_and_b32_e32 v196, 0xffff0000, v196
	v_fmac_f32_e32 v232, v37, v196
	v_lshlrev_b32_e32 v201, 16, v233
	v_lshlrev_b32_e32 v136, 16, v197
	v_fmac_f32_e32 v201, v38, v136
	v_and_b32_e32 v233, 0xffff0000, v233
	v_and_b32_e32 v197, 0xffff0000, v197
	v_fmac_f32_e32 v233, v39, v197
	v_lshlrev_b32_e32 v244, 16, v234
	v_lshlrev_b32_e32 v136, 16, v198
	v_fmac_f32_e32 v244, v32, v136
	v_and_b32_e32 v234, 0xffff0000, v234
	v_and_b32_e32 v198, 0xffff0000, v198
	v_fmac_f32_e32 v234, v33, v198
	v_lshlrev_b32_e32 v245, 16, v235
	v_lshlrev_b32_e32 v136, 16, v199
	v_fmac_f32_e32 v245, v34, v136
	v_and_b32_e32 v235, 0xffff0000, v235
	v_and_b32_e32 v199, 0xffff0000, v199
	v_fmac_f32_e32 v235, v35, v199
	v_cvt_pk_bf16_f32 v232, v200, v232
	v_cvt_pk_bf16_f32 v233, v201, v233
	v_cvt_pk_bf16_f32 v234, v244, v234
	v_cvt_pk_bf16_f32 v235, v245, v235
	global_store_dwordx4 v[158:159], v[232:235], off offset:256
	v_add_u32_e32 v132, s6, v166
	v_ashrrev_i32_e32 v133, 31, v132
	v_lshlrev_b64 v[158:159], 11, v[132:133]
	v_lshl_add_u64 v[158:159], s[46:47], 0, v[158:159]
	v_lshl_add_u64 v[158:159], v[158:159], 0, v[128:129]
	s_waitcnt vmcnt(13)
	v_lshlrev_b32_e32 v200, 16, v236
	v_lshlrev_b32_e32 v136, 16, v204
	v_fmac_f32_e32 v200, v28, v136
	v_and_b32_e32 v236, 0xffff0000, v236
	v_and_b32_e32 v204, 0xffff0000, v204
	v_fmac_f32_e32 v236, v29, v204
	v_lshlrev_b32_e32 v201, 16, v237
	v_lshlrev_b32_e32 v136, 16, v205
	v_fmac_f32_e32 v201, v30, v136
	v_and_b32_e32 v237, 0xffff0000, v237
	v_and_b32_e32 v205, 0xffff0000, v205
	v_fmac_f32_e32 v237, v31, v205
	v_lshlrev_b32_e32 v244, 16, v238
	v_lshlrev_b32_e32 v136, 16, v206
	v_fmac_f32_e32 v244, v24, v136
	v_and_b32_e32 v238, 0xffff0000, v238
	v_and_b32_e32 v206, 0xffff0000, v206
	v_fmac_f32_e32 v238, v25, v206
	v_lshlrev_b32_e32 v245, 16, v239
	v_lshlrev_b32_e32 v136, 16, v207
	v_fmac_f32_e32 v245, v26, v136
	v_and_b32_e32 v239, 0xffff0000, v239
	v_and_b32_e32 v207, 0xffff0000, v207
	v_fmac_f32_e32 v239, v27, v207
	v_cvt_pk_bf16_f32 v236, v200, v236
	v_cvt_pk_bf16_f32 v237, v201, v237
	v_cvt_pk_bf16_f32 v238, v244, v238
	v_cvt_pk_bf16_f32 v239, v245, v239
	global_store_dwordx4 v[158:159], v[236:239], off
	v_add_u32_e32 v132, s6, v166
	v_ashrrev_i32_e32 v133, 31, v132
	v_lshlrev_b64 v[158:159], 11, v[132:133]
	v_lshl_add_u64 v[158:159], s[46:47], 0, v[158:159]
	v_lshl_add_u64 v[158:159], v[158:159], 0, v[128:129]
	s_waitcnt vmcnt(11)
	v_lshlrev_b32_e32 v200, 16, v240
	v_lshlrev_b32_e32 v136, 16, v208
	v_fmac_f32_e32 v200, v20, v136
	v_and_b32_e32 v240, 0xffff0000, v240
	v_and_b32_e32 v208, 0xffff0000, v208
	v_fmac_f32_e32 v240, v21, v208
	v_lshlrev_b32_e32 v201, 16, v241
	v_lshlrev_b32_e32 v136, 16, v209
	v_fmac_f32_e32 v201, v22, v136
	v_and_b32_e32 v241, 0xffff0000, v241
	v_and_b32_e32 v209, 0xffff0000, v209
	v_fmac_f32_e32 v241, v23, v209
	v_lshlrev_b32_e32 v244, 16, v242
	v_lshlrev_b32_e32 v136, 16, v210
	v_fmac_f32_e32 v244, v16, v136
	v_and_b32_e32 v242, 0xffff0000, v242
	v_and_b32_e32 v210, 0xffff0000, v210
	v_fmac_f32_e32 v242, v17, v210
	v_lshlrev_b32_e32 v245, 16, v243
	v_lshlrev_b32_e32 v136, 16, v211
	v_fmac_f32_e32 v245, v18, v136
	v_and_b32_e32 v243, 0xffff0000, v243
	v_and_b32_e32 v211, 0xffff0000, v211
	v_fmac_f32_e32 v243, v19, v211
	v_cvt_pk_bf16_f32 v240, v200, v240
	v_cvt_pk_bf16_f32 v241, v201, v241
	v_cvt_pk_bf16_f32 v242, v244, v242
	v_cvt_pk_bf16_f32 v243, v245, v243
	global_store_dwordx4 v[158:159], v[240:243], off offset:256
	v_add_u32_e32 v132, s6, v167
	v_ashrrev_i32_e32 v133, 31, v132
	v_lshlrev_b64 v[158:159], 11, v[132:133]
	v_lshl_add_u64 v[158:159], s[46:47], 0, v[158:159]
	v_lshl_add_u64 v[158:159], v[158:159], 0, v[128:129]
	s_waitcnt vmcnt(9)
	v_lshlrev_b32_e32 v200, 16, v150
	v_lshlrev_b32_e32 v136, 16, v212
	v_fmac_f32_e32 v200, v12, v136
	v_and_b32_e32 v150, 0xffff0000, v150
	v_and_b32_e32 v212, 0xffff0000, v212
	v_fmac_f32_e32 v150, v13, v212
	v_lshlrev_b32_e32 v201, 16, v151
	v_lshlrev_b32_e32 v136, 16, v213
	v_fmac_f32_e32 v201, v14, v136
	v_and_b32_e32 v151, 0xffff0000, v151
	v_and_b32_e32 v213, 0xffff0000, v213
	v_fmac_f32_e32 v151, v15, v213
	v_lshlrev_b32_e32 v244, 16, v152
	v_lshlrev_b32_e32 v136, 16, v214
	v_fmac_f32_e32 v244, v8, v136
	v_and_b32_e32 v152, 0xffff0000, v152
	v_and_b32_e32 v214, 0xffff0000, v214
	v_fmac_f32_e32 v152, v9, v214
	v_lshlrev_b32_e32 v245, 16, v153
	v_lshlrev_b32_e32 v136, 16, v215
	v_fmac_f32_e32 v245, v10, v136
	v_and_b32_e32 v153, 0xffff0000, v153
	v_and_b32_e32 v215, 0xffff0000, v215
	v_fmac_f32_e32 v153, v11, v215
	v_cvt_pk_bf16_f32 v150, v200, v150
	v_cvt_pk_bf16_f32 v151, v201, v151
	v_cvt_pk_bf16_f32 v152, v244, v152
	v_cvt_pk_bf16_f32 v153, v245, v153
	global_store_dwordx4 v[158:159], v[150:153], off
	v_add_u32_e32 v132, s6, v167
	v_ashrrev_i32_e32 v133, 31, v132
	v_lshlrev_b64 v[158:159], 11, v[132:133]
	v_lshl_add_u64 v[158:159], s[46:47], 0, v[158:159]
	v_lshl_add_u64 v[158:159], v[158:159], 0, v[128:129]
	s_waitcnt vmcnt(7)
	v_lshlrev_b32_e32 v200, 16, v154
	v_lshlrev_b32_e32 v136, 16, v216
	v_fmac_f32_e32 v200, v4, v136
	v_and_b32_e32 v154, 0xffff0000, v154
	v_and_b32_e32 v216, 0xffff0000, v216
	v_fmac_f32_e32 v154, v5, v216
	v_lshlrev_b32_e32 v201, 16, v155
	v_lshlrev_b32_e32 v136, 16, v217
	v_fmac_f32_e32 v201, v6, v136
	v_and_b32_e32 v155, 0xffff0000, v155
	v_and_b32_e32 v217, 0xffff0000, v217
	v_fmac_f32_e32 v155, v7, v217
	v_lshlrev_b32_e32 v244, 16, v156
	v_lshlrev_b32_e32 v136, 16, v218
	v_fmac_f32_e32 v244, v0, v136
	v_and_b32_e32 v156, 0xffff0000, v156
	v_and_b32_e32 v218, 0xffff0000, v218
	v_fmac_f32_e32 v156, v1, v218
	v_lshlrev_b32_e32 v245, 16, v157
	v_lshlrev_b32_e32 v136, 16, v219
	v_fmac_f32_e32 v245, v2, v136
	v_and_b32_e32 v157, 0xffff0000, v157
	v_and_b32_e32 v219, 0xffff0000, v219
	v_fmac_f32_e32 v157, v3, v219
	v_cvt_pk_bf16_f32 v154, v200, v154
	v_cvt_pk_bf16_f32 v155, v201, v155
	v_cvt_pk_bf16_f32 v156, v244, v156
	v_cvt_pk_bf16_f32 v157, v245, v157
	global_store_dwordx4 v[158:159], v[154:157], off offset:256
	v_readlane_b32 s10, v253, 4
	v_readlane_b32 s11, v253, 5

.LBB0_1635:
	s_cmp_lt_i32 s66, 2
	s_mov_b64 s[6:7], -1
	s_cbranch_scc1 .LBB0_1641
	s_cmp_gt_i32 s66, 2
	s_cbranch_scc0 .LBB0_1638
	s_lshl_b32 s6, s83, 8
	v_add_u32_e32 v130, s6, v161
	v_lshl_or_b32 v128, s82, 8, v168
	v_ashrrev_i32_e32 v129, 31, v128
	v_lshlrev_b64 v[128:129], 1, v[128:129]
	v_mov_b32_e32 v132, v130
	v_ashrrev_i32_e32 v133, 31, v132
	v_lshlrev_b64 v[134:135], 12, v[132:133]
	v_lshl_add_u64 v[134:135], s[96:97], 0, v[134:135]
	v_lshl_add_u64 v[134:135], v[134:135], 0, v[128:129]
	global_load_dwordx4 v[170:173], v[134:135], off
	global_load_dwordx4 v[188:191], v[134:135], off offset:256
	v_or_b32_e32 v132, 16, v130
	v_ashrrev_i32_e32 v133, 31, v132
	v_lshlrev_b64 v[134:135], 12, v[132:133]
	v_lshl_add_u64 v[134:135], s[96:97], 0, v[134:135]
	v_lshl_add_u64 v[134:135], v[134:135], 0, v[128:129]
	global_load_dwordx4 v[192:195], v[134:135], off
	global_load_dwordx4 v[196:199], v[134:135], off offset:256
	v_or_b32_e32 v132, 32, v130
	v_ashrrev_i32_e32 v133, 31, v132
	v_lshlrev_b64 v[134:135], 12, v[132:133]
	v_lshl_add_u64 v[134:135], s[96:97], 0, v[134:135]
	v_lshl_add_u64 v[134:135], v[134:135], 0, v[128:129]
	global_load_dwordx4 v[204:207], v[134:135], off
	global_load_dwordx4 v[208:211], v[134:135], off offset:256
	v_or_b32_e32 v132, 48, v130
	v_ashrrev_i32_e32 v133, 31, v132
	v_lshlrev_b64 v[134:135], 12, v[132:133]
	v_lshl_add_u64 v[134:135], s[96:97], 0, v[134:135]
	v_lshl_add_u64 v[134:135], v[134:135], 0, v[128:129]
	global_load_dwordx4 v[212:215], v[134:135], off
	global_load_dwordx4 v[216:219], v[134:135], off offset:256
	v_add_u32_e32 v132, s6, v164
	v_ashrrev_i32_e32 v133, 31, v132
	v_lshlrev_b64 v[134:135], 12, v[132:133]
	v_lshl_add_u64 v[134:135], s[96:97], 0, v[134:135]
	v_lshl_add_u64 v[134:135], v[134:135], 0, v[128:129]
	global_load_dwordx4 v[220:223], v[134:135], off
	global_load_dwordx4 v[224:227], v[134:135], off offset:256
	v_add_u32_e32 v132, s6, v165
	v_ashrrev_i32_e32 v133, 31, v132
	v_lshlrev_b64 v[134:135], 12, v[132:133]
	v_lshl_add_u64 v[134:135], s[96:97], 0, v[134:135]
	v_lshl_add_u64 v[134:135], v[134:135], 0, v[128:129]
	global_load_dwordx4 v[228:231], v[134:135], off
	global_load_dwordx4 v[232:235], v[134:135], off offset:256
	v_add_u32_e32 v132, s6, v166
	v_ashrrev_i32_e32 v133, 31, v132
	v_lshlrev_b64 v[134:135], 12, v[132:133]
	v_lshl_add_u64 v[134:135], s[96:97], 0, v[134:135]
	v_lshl_add_u64 v[134:135], v[134:135], 0, v[128:129]
	global_load_dwordx4 v[236:239], v[134:135], off
	global_load_dwordx4 v[240:243], v[134:135], off offset:256
	v_add_u32_e32 v132, s6, v167
	v_ashrrev_i32_e32 v133, 31, v132
	v_lshlrev_b64 v[134:135], 12, v[132:133]
	v_lshl_add_u64 v[134:135], s[96:97], 0, v[134:135]
	v_lshl_add_u64 v[134:135], v[134:135], 0, v[128:129]
	global_load_dwordx4 v[150:153], v[134:135], off
	global_load_dwordx4 v[154:157], v[134:135], off offset:256
	v_mov_b32_e32 v132, v130
	v_ashrrev_i32_e32 v133, 31, v132
	v_lshlrev_b64 v[158:159], 11, v[132:133]
	v_lshl_add_u64 v[158:159], s[46:47], 0, v[158:159]
	v_lshl_add_u64 v[158:159], v[158:159], 0, v[128:129]
	s_waitcnt vmcnt(15)
	v_lshlrev_b32_e32 v200, 16, v170
	v_and_b32_e32 v170, 0xffff0000, v170
	v_lshlrev_b32_e32 v201, 16, v171
	v_and_b32_e32 v171, 0xffff0000, v171
	v_lshlrev_b32_e32 v244, 16, v172
	v_and_b32_e32 v172, 0xffff0000, v172
	v_lshlrev_b32_e32 v245, 16, v173
	v_and_b32_e32 v173, 0xffff0000, v173
	v_mul_f32_e32 v200, v124, v200
	v_mul_f32_e32 v170, v125, v170
	v_mul_f32_e32 v201, v126, v201
	v_mul_f32_e32 v171, v127, v171
	v_mul_f32_e32 v244, v120, v244
	v_mul_f32_e32 v172, v121, v172
	v_mul_f32_e32 v245, v122, v245
	v_mul_f32_e32 v173, v123, v173
	v_cvt_pk_bf16_f32 v170, v200, v170
	v_cvt_pk_bf16_f32 v171, v201, v171
	v_cvt_pk_bf16_f32 v172, v244, v172
	v_cvt_pk_bf16_f32 v173, v245, v173
	global_store_dwordx4 v[158:159], v[170:173], off
	s_waitcnt vmcnt(15)
	v_lshlrev_b32_e32 v200, 16, v188
	v_and_b32_e32 v188, 0xffff0000, v188
	v_lshlrev_b32_e32 v201, 16, v189
	v_and_b32_e32 v189, 0xffff0000, v189
	v_lshlrev_b32_e32 v244, 16, v190
	v_and_b32_e32 v190, 0xffff0000, v190
	v_lshlrev_b32_e32 v245, 16, v191
	v_and_b32_e32 v191, 0xffff0000, v191
	v_mul_f32_e32 v200, v116, v200
	v_mul_f32_e32 v188, v117, v188
	v_mul_f32_e32 v201, v118, v201
	v_mul_f32_e32 v189, v119, v189
	v_mul_f32_e32 v244, v112, v244
	v_mul_f32_e32 v190, v113, v190
	v_mul_f32_e32 v245, v114, v245
	v_mul_f32_e32 v191, v115, v191
	v_cvt_pk_bf16_f32 v188, v200, v188
	v_cvt_pk_bf16_f32 v189, v201, v189
	v_cvt_pk_bf16_f32 v190, v244, v190
	v_cvt_pk_bf16_f32 v191, v245, v191
	global_store_dwordx4 v[158:159], v[188:191], off offset:256
	v_or_b32_e32 v132, 16, v130
	v_ashrrev_i32_e32 v133, 31, v132
	v_lshlrev_b64 v[158:159], 11, v[132:133]
	v_lshl_add_u64 v[158:159], s[46:47], 0, v[158:159]
	v_lshl_add_u64 v[158:159], v[158:159], 0, v[128:129]
	s_waitcnt vmcnt(15)
	v_lshlrev_b32_e32 v200, 16, v192
	v_and_b32_e32 v192, 0xffff0000, v192
	v_lshlrev_b32_e32 v201, 16, v193
	v_and_b32_e32 v193, 0xffff0000, v193
	v_lshlrev_b32_e32 v244, 16, v194
	v_and_b32_e32 v194, 0xffff0000, v194
	v_lshlrev_b32_e32 v245, 16, v195
	v_and_b32_e32 v195, 0xffff0000, v195
	v_mul_f32_e32 v200, v108, v200
	v_mul_f32_e32 v192, v109, v192
	v_mul_f32_e32 v201, v110, v201
	v_mul_f32_e32 v193, v111, v193
	v_mul_f32_e32 v244, v104, v244
	v_mul_f32_e32 v194, v105, v194
	v_mul_f32_e32 v245, v106, v245
	v_mul_f32_e32 v195, v107, v195
	v_cvt_pk_bf16_f32 v192, v200, v192
	v_cvt_pk_bf16_f32 v193, v201, v193
	v_cvt_pk_bf16_f32 v194, v244, v194
	v_cvt_pk_bf16_f32 v195, v245, v195
	global_store_dwordx4 v[158:159], v[192:195], off
	s_waitcnt vmcnt(15)
	v_lshlrev_b32_e32 v200, 16, v196
	v_and_b32_e32 v196, 0xffff0000, v196
	v_lshlrev_b32_e32 v201, 16, v197
	v_and_b32_e32 v197, 0xffff0000, v197
	v_lshlrev_b32_e32 v244, 16, v198
	v_and_b32_e32 v198, 0xffff0000, v198
	v_lshlrev_b32_e32 v245, 16, v199
	v_and_b32_e32 v199, 0xffff0000, v199
	v_mul_f32_e32 v200, v100, v200
	v_mul_f32_e32 v196, v101, v196
	v_mul_f32_e32 v201, v102, v201
	v_mul_f32_e32 v197, v103, v197
	v_mul_f32_e32 v244, v96, v244
	v_mul_f32_e32 v198, v97, v198
	v_mul_f32_e32 v245, v98, v245
	v_mul_f32_e32 v199, v99, v199
	v_cvt_pk_bf16_f32 v196, v200, v196
	v_cvt_pk_bf16_f32 v197, v201, v197
	v_cvt_pk_bf16_f32 v198, v244, v198
	v_cvt_pk_bf16_f32 v199, v245, v199
	global_store_dwordx4 v[158:159], v[196:199], off offset:256
	v_or_b32_e32 v132, 32, v130
	v_ashrrev_i32_e32 v133, 31, v132
	v_lshlrev_b64 v[158:159], 11, v[132:133]
	v_lshl_add_u64 v[158:159], s[46:47], 0, v[158:159]
	v_lshl_add_u64 v[158:159], v[158:159], 0, v[128:129]
	s_waitcnt vmcnt(15)
	v_lshlrev_b32_e32 v200, 16, v204
	v_and_b32_e32 v204, 0xffff0000, v204
	v_lshlrev_b32_e32 v201, 16, v205
	v_and_b32_e32 v205, 0xffff0000, v205
	v_lshlrev_b32_e32 v244, 16, v206
	v_and_b32_e32 v206, 0xffff0000, v206
	v_lshlrev_b32_e32 v245, 16, v207
	v_and_b32_e32 v207, 0xffff0000, v207
	v_mul_f32_e32 v200, v92, v200
	v_mul_f32_e32 v204, v93, v204
	v_mul_f32_e32 v201, v94, v201
	v_mul_f32_e32 v205, v95, v205
	v_mul_f32_e32 v244, v88, v244
	v_mul_f32_e32 v206, v89, v206
	v_mul_f32_e32 v245, v90, v245
	v_mul_f32_e32 v207, v91, v207
	v_cvt_pk_bf16_f32 v204, v200, v204
	v_cvt_pk_bf16_f32 v205, v201, v205
	v_cvt_pk_bf16_f32 v206, v244, v206
	v_cvt_pk_bf16_f32 v207, v245, v207
	global_store_dwordx4 v[158:159], v[204:207], off
	s_waitcnt vmcnt(15)
	v_lshlrev_b32_e32 v200, 16, v208
	v_and_b32_e32 v208, 0xffff0000, v208
	v_lshlrev_b32_e32 v201, 16, v209
	v_and_b32_e32 v209, 0xffff0000, v209
	v_lshlrev_b32_e32 v244, 16, v210
	v_and_b32_e32 v210, 0xffff0000, v210
	v_lshlrev_b32_e32 v245, 16, v211
	v_and_b32_e32 v211, 0xffff0000, v211
	v_mul_f32_e32 v200, v84, v200
	v_mul_f32_e32 v208, v85, v208
	v_mul_f32_e32 v201, v86, v201
	v_mul_f32_e32 v209, v87, v209
	v_mul_f32_e32 v244, v80, v244
	v_mul_f32_e32 v210, v81, v210
	v_mul_f32_e32 v245, v82, v245
	v_mul_f32_e32 v211, v83, v211
	v_cvt_pk_bf16_f32 v208, v200, v208
	v_cvt_pk_bf16_f32 v209, v201, v209
	v_cvt_pk_bf16_f32 v210, v244, v210
	v_cvt_pk_bf16_f32 v211, v245, v211
	global_store_dwordx4 v[158:159], v[208:211], off offset:256
	v_or_b32_e32 v132, 48, v130
	v_ashrrev_i32_e32 v133, 31, v132
	v_lshlrev_b64 v[158:159], 11, v[132:133]
	v_lshl_add_u64 v[158:159], s[46:47], 0, v[158:159]
	v_lshl_add_u64 v[158:159], v[158:159], 0, v[128:129]
	s_waitcnt vmcnt(15)
	v_lshlrev_b32_e32 v200, 16, v212
	v_and_b32_e32 v212, 0xffff0000, v212
	v_lshlrev_b32_e32 v201, 16, v213
	v_and_b32_e32 v213, 0xffff0000, v213
	v_lshlrev_b32_e32 v244, 16, v214
	v_and_b32_e32 v214, 0xffff0000, v214
	v_lshlrev_b32_e32 v245, 16, v215
	v_and_b32_e32 v215, 0xffff0000, v215
	v_mul_f32_e32 v200, v76, v200
	v_mul_f32_e32 v212, v77, v212
	v_mul_f32_e32 v201, v78, v201
	v_mul_f32_e32 v213, v79, v213
	v_mul_f32_e32 v244, v72, v244
	v_mul_f32_e32 v214, v73, v214
	v_mul_f32_e32 v245, v74, v245
	v_mul_f32_e32 v215, v75, v215
	v_cvt_pk_bf16_f32 v212, v200, v212
	v_cvt_pk_bf16_f32 v213, v201, v213
	v_cvt_pk_bf16_f32 v214, v244, v214
	v_cvt_pk_bf16_f32 v215, v245, v215
	global_store_dwordx4 v[158:159], v[212:215], off
	s_waitcnt vmcnt(15)
	v_lshlrev_b32_e32 v200, 16, v216
	v_and_b32_e32 v216, 0xffff0000, v216
	v_lshlrev_b32_e32 v201, 16, v217
	v_and_b32_e32 v217, 0xffff0000, v217
	v_lshlrev_b32_e32 v244, 16, v218
	v_and_b32_e32 v218, 0xffff0000, v218
	v_lshlrev_b32_e32 v245, 16, v219
	v_and_b32_e32 v219, 0xffff0000, v219
	v_mul_f32_e32 v200, v68, v200
	v_mul_f32_e32 v216, v69, v216
	v_mul_f32_e32 v201, v70, v201
	v_mul_f32_e32 v217, v71, v217
	v_mul_f32_e32 v244, v64, v244
	v_mul_f32_e32 v218, v65, v218
	v_mul_f32_e32 v245, v66, v245
	v_mul_f32_e32 v219, v67, v219
	v_cvt_pk_bf16_f32 v216, v200, v216
	v_cvt_pk_bf16_f32 v217, v201, v217
	v_cvt_pk_bf16_f32 v218, v244, v218
	v_cvt_pk_bf16_f32 v219, v245, v219
	global_store_dwordx4 v[158:159], v[216:219], off offset:256
	v_add_u32_e32 v132, s6, v164
	v_ashrrev_i32_e32 v133, 31, v132
	v_lshlrev_b64 v[158:159], 11, v[132:133]
	v_lshl_add_u64 v[158:159], s[46:47], 0, v[158:159]
	v_lshl_add_u64 v[158:159], v[158:159], 0, v[128:129]
	s_waitcnt vmcnt(15)
	v_lshlrev_b32_e32 v200, 16, v220
	v_and_b32_e32 v220, 0xffff0000, v220
	v_lshlrev_b32_e32 v201, 16, v221
	v_and_b32_e32 v221, 0xffff0000, v221
	v_lshlrev_b32_e32 v244, 16, v222
	v_and_b32_e32 v222, 0xffff0000, v222
	v_lshlrev_b32_e32 v245, 16, v223
	v_and_b32_e32 v223, 0xffff0000, v223
	v_mul_f32_e32 v200, v60, v200
	v_mul_f32_e32 v220, v61, v220
	v_mul_f32_e32 v201, v62, v201
	v_mul_f32_e32 v221, v63, v221
	v_mul_f32_e32 v244, v56, v244
	v_mul_f32_e32 v222, v57, v222
	v_mul_f32_e32 v245, v58, v245
	v_mul_f32_e32 v223, v59, v223
	v_cvt_pk_bf16_f32 v220, v200, v220
	v_cvt_pk_bf16_f32 v221, v201, v221
	v_cvt_pk_bf16_f32 v222, v244, v222
	v_cvt_pk_bf16_f32 v223, v245, v223
	global_store_dwordx4 v[158:159], v[220:223], off
	s_waitcnt vmcnt(15)
	v_lshlrev_b32_e32 v200, 16, v224
	v_and_b32_e32 v224, 0xffff0000, v224
	v_lshlrev_b32_e32 v201, 16, v225
	v_and_b32_e32 v225, 0xffff0000, v225
	v_lshlrev_b32_e32 v244, 16, v226
	v_and_b32_e32 v226, 0xffff0000, v226
	v_lshlrev_b32_e32 v245, 16, v227
	v_and_b32_e32 v227, 0xffff0000, v227
	v_mul_f32_e32 v200, v52, v200
	v_mul_f32_e32 v224, v53, v224
	v_mul_f32_e32 v201, v54, v201
	v_mul_f32_e32 v225, v55, v225
	v_mul_f32_e32 v244, v48, v244
	v_mul_f32_e32 v226, v49, v226
	v_mul_f32_e32 v245, v50, v245
	v_mul_f32_e32 v227, v51, v227
	v_cvt_pk_bf16_f32 v224, v200, v224
	v_cvt_pk_bf16_f32 v225, v201, v225
	v_cvt_pk_bf16_f32 v226, v244, v226
	v_cvt_pk_bf16_f32 v227, v245, v227
	global_store_dwordx4 v[158:159], v[224:227], off offset:256
	v_add_u32_e32 v132, s6, v165
	v_ashrrev_i32_e32 v133, 31, v132
	v_lshlrev_b64 v[158:159], 11, v[132:133]
	v_lshl_add_u64 v[158:159], s[46:47], 0, v[158:159]
	v_lshl_add_u64 v[158:159], v[158:159], 0, v[128:129]
	s_waitcnt vmcnt(15)
	v_lshlrev_b32_e32 v200, 16, v228
	v_and_b32_e32 v228, 0xffff0000, v228
	v_lshlrev_b32_e32 v201, 16, v229
	v_and_b32_e32 v229, 0xffff0000, v229
	v_lshlrev_b32_e32 v244, 16, v230
	v_and_b32_e32 v230, 0xffff0000, v230
	v_lshlrev_b32_e32 v245, 16, v231
	v_and_b32_e32 v231, 0xffff0000, v231
	v_mul_f32_e32 v200, v44, v200
	v_mul_f32_e32 v228, v45, v228
	v_mul_f32_e32 v201, v46, v201
	v_mul_f32_e32 v229, v47, v229
	v_mul_f32_e32 v244, v40, v244
	v_mul_f32_e32 v230, v41, v230
	v_mul_f32_e32 v245, v42, v245
	v_mul_f32_e32 v231, v43, v231
	v_cvt_pk_bf16_f32 v228, v200, v228
	v_cvt_pk_bf16_f32 v229, v201, v229
	v_cvt_pk_bf16_f32 v230, v244, v230
	v_cvt_pk_bf16_f32 v231, v245, v231
	global_store_dwordx4 v[158:159], v[228:231], off
	s_waitcnt vmcnt(15)
	v_lshlrev_b32_e32 v200, 16, v232
	v_and_b32_e32 v232, 0xffff0000, v232
	v_lshlrev_b32_e32 v201, 16, v233
	v_and_b32_e32 v233, 0xffff0000, v233
	v_lshlrev_b32_e32 v244, 16, v234
	v_and_b32_e32 v234, 0xffff0000, v234
	v_lshlrev_b32_e32 v245, 16, v235
	v_and_b32_e32 v235, 0xffff0000, v235
	v_mul_f32_e32 v200, v36, v200
	v_mul_f32_e32 v232, v37, v232
	v_mul_f32_e32 v201, v38, v201
	v_mul_f32_e32 v233, v39, v233
	v_mul_f32_e32 v244, v32, v244
	v_mul_f32_e32 v234, v33, v234
	v_mul_f32_e32 v245, v34, v245
	v_mul_f32_e32 v235, v35, v235
	v_cvt_pk_bf16_f32 v232, v200, v232
	v_cvt_pk_bf16_f32 v233, v201, v233
	v_cvt_pk_bf16_f32 v234, v244, v234
	v_cvt_pk_bf16_f32 v235, v245, v235
	global_store_dwordx4 v[158:159], v[232:235], off offset:256
	v_add_u32_e32 v132, s6, v166
	v_ashrrev_i32_e32 v133, 31, v132
	v_lshlrev_b64 v[158:159], 11, v[132:133]
	v_lshl_add_u64 v[158:159], s[46:47], 0, v[158:159]
	v_lshl_add_u64 v[158:159], v[158:159], 0, v[128:129]
	s_waitcnt vmcnt(15)
	v_lshlrev_b32_e32 v200, 16, v236
	v_and_b32_e32 v236, 0xffff0000, v236
	v_lshlrev_b32_e32 v201, 16, v237
	v_and_b32_e32 v237, 0xffff0000, v237
	v_lshlrev_b32_e32 v244, 16, v238
	v_and_b32_e32 v238, 0xffff0000, v238
	v_lshlrev_b32_e32 v245, 16, v239
	v_and_b32_e32 v239, 0xffff0000, v239
	v_mul_f32_e32 v200, v28, v200
	v_mul_f32_e32 v236, v29, v236
	v_mul_f32_e32 v201, v30, v201
	v_mul_f32_e32 v237, v31, v237
	v_mul_f32_e32 v244, v24, v244
	v_mul_f32_e32 v238, v25, v238
	v_mul_f32_e32 v245, v26, v245
	v_mul_f32_e32 v239, v27, v239
	v_cvt_pk_bf16_f32 v236, v200, v236
	v_cvt_pk_bf16_f32 v237, v201, v237
	v_cvt_pk_bf16_f32 v238, v244, v238
	v_cvt_pk_bf16_f32 v239, v245, v239
	global_store_dwordx4 v[158:159], v[236:239], off
	s_waitcnt vmcnt(15)
	v_lshlrev_b32_e32 v200, 16, v240
	v_and_b32_e32 v240, 0xffff0000, v240
	v_lshlrev_b32_e32 v201, 16, v241
	v_and_b32_e32 v241, 0xffff0000, v241
	v_lshlrev_b32_e32 v244, 16, v242
	v_and_b32_e32 v242, 0xffff0000, v242
	v_lshlrev_b32_e32 v245, 16, v243
	v_and_b32_e32 v243, 0xffff0000, v243
	v_mul_f32_e32 v200, v20, v200
	v_mul_f32_e32 v240, v21, v240
	v_mul_f32_e32 v201, v22, v201
	v_mul_f32_e32 v241, v23, v241
	v_mul_f32_e32 v244, v16, v244
	v_mul_f32_e32 v242, v17, v242
	v_mul_f32_e32 v245, v18, v245
	v_mul_f32_e32 v243, v19, v243
	v_cvt_pk_bf16_f32 v240, v200, v240
	v_cvt_pk_bf16_f32 v241, v201, v241
	v_cvt_pk_bf16_f32 v242, v244, v242
	v_cvt_pk_bf16_f32 v243, v245, v243
	global_store_dwordx4 v[158:159], v[240:243], off offset:256
	v_add_u32_e32 v132, s6, v167
	v_ashrrev_i32_e32 v133, 31, v132
	v_lshlrev_b64 v[158:159], 11, v[132:133]
	v_lshl_add_u64 v[158:159], s[46:47], 0, v[158:159]
	v_lshl_add_u64 v[158:159], v[158:159], 0, v[128:129]
	s_waitcnt vmcnt(15)
	v_lshlrev_b32_e32 v200, 16, v150
	v_and_b32_e32 v150, 0xffff0000, v150
	v_lshlrev_b32_e32 v201, 16, v151
	v_and_b32_e32 v151, 0xffff0000, v151
	v_lshlrev_b32_e32 v244, 16, v152
	v_and_b32_e32 v152, 0xffff0000, v152
	v_lshlrev_b32_e32 v245, 16, v153
	v_and_b32_e32 v153, 0xffff0000, v153
	v_mul_f32_e32 v200, v12, v200
	v_mul_f32_e32 v150, v13, v150
	v_mul_f32_e32 v201, v14, v201
	v_mul_f32_e32 v151, v15, v151
	v_mul_f32_e32 v244, v8, v244
	v_mul_f32_e32 v152, v9, v152
	v_mul_f32_e32 v245, v10, v245
	v_mul_f32_e32 v153, v11, v153
	v_cvt_pk_bf16_f32 v150, v200, v150
	v_cvt_pk_bf16_f32 v151, v201, v151
	v_cvt_pk_bf16_f32 v152, v244, v152
	v_cvt_pk_bf16_f32 v153, v245, v153
	global_store_dwordx4 v[158:159], v[150:153], off
	s_waitcnt vmcnt(15)
	v_lshlrev_b32_e32 v200, 16, v154
	v_and_b32_e32 v154, 0xffff0000, v154
	v_lshlrev_b32_e32 v201, 16, v155
	v_and_b32_e32 v155, 0xffff0000, v155
	v_lshlrev_b32_e32 v244, 16, v156
	v_and_b32_e32 v156, 0xffff0000, v156
	v_lshlrev_b32_e32 v245, 16, v157
	v_and_b32_e32 v157, 0xffff0000, v157
	v_mul_f32_e32 v200, v4, v200
	v_mul_f32_e32 v154, v5, v154
	v_mul_f32_e32 v201, v6, v201
	v_mul_f32_e32 v155, v7, v155
	v_mul_f32_e32 v244, v0, v244
	v_mul_f32_e32 v156, v1, v156
	v_mul_f32_e32 v245, v2, v245
	v_mul_f32_e32 v157, v3, v157
	v_cvt_pk_bf16_f32 v154, v200, v154
	v_cvt_pk_bf16_f32 v155, v201, v155
	v_cvt_pk_bf16_f32 v156, v244, v156
	v_cvt_pk_bf16_f32 v157, v245, v157
	global_store_dwordx4 v[158:159], v[154:157], off offset:256
	s_mov_b64 s[6:7], 0
